# v24 plus: the first epilogue row's sums of squares are fetched from inside the K-loop's last iteration (spare VGPRs v228-245)
# speedup vs baseline: 1.0111x; 1.0111x over previous
.LBB0_252:
	ds_read_b128 v[156:159], v149
	ds_read_b128 v[160:163], v149 offset:1024
	ds_read_b128 v[164:167], v149 offset:2048
	ds_read_b128 v[168:171], v149 offset:3072
	ds_read_b128 v[172:175], v150
	ds_read_b128 v[176:179], v150 offset:1024
	ds_read_b128 v[180:183], v150 offset:2048
	ds_read_b128 v[184:187], v150 offset:3072
	s_add_u32 s26, s24, 0xfffc0080
	s_addc_u32 s27, s25, -1
	s_cmp_eq_u32 s57, 12
	s_cselect_b32 s29, s19, s27
	s_cselect_b32 s28, s53, s26
	s_cselect_b32 s27, s17, s56
	s_cselect_b32 s26, s54, s55
	v_lshl_add_u64 v[146:147], s[24:25], 0, v[138:139]
	s_add_i32 m0, s38, 0xc000
	ds_read_b128 v[188:191], v151
	ds_read_b128 v[192:195], v151 offset:1024
	ds_read_b128 v[196:199], v151 offset:2048
	ds_read_b128 v[200:203], v151 offset:3072
	ds_read_b128 v[204:207], v151 offset:4096
	ds_read_b128 v[208:211], v151 offset:5120
	ds_read_b128 v[212:215], v151 offset:6144
	ds_read_b128 v[216:219], v151 offset:7168
	global_load_lds_dwordx4 v[146:147], off
	v_lshl_add_u64 v[146:147], s[24:25], 0, v[140:141]
	s_add_i32 m0, s38, 0xe000
	s_nop 0
	global_load_lds_dwordx4 v[146:147], off
	s_waitcnt vmcnt(8)
	s_waitcnt lgkmcnt(0)
	s_barrier
	s_setprio 1
	s_waitcnt lgkmcnt(0)
	v_mfma_f32_16x16x32_bf16 v[122:125], v[156:159], v[188:191], v[122:125]
	v_mfma_f32_16x16x32_bf16 v[114:117], v[164:167], v[188:191], v[114:117]
	v_mfma_f32_16x16x32_bf16 v[106:109], v[156:159], v[196:199], v[106:109]
	v_mfma_f32_16x16x32_bf16 v[102:105], v[164:167], v[196:199], v[102:105]
	v_mfma_f32_16x16x32_bf16 v[90:93], v[156:159], v[204:207], v[90:93]
	v_mfma_f32_16x16x32_bf16 v[86:89], v[164:167], v[204:207], v[86:89]
	v_mfma_f32_16x16x32_bf16 v[74:77], v[156:159], v[212:215], v[74:77]
	v_mfma_f32_16x16x32_bf16 v[70:73], v[164:167], v[212:215], v[70:73]
	v_mfma_f32_16x16x32_bf16 v[122:125], v[160:163], v[192:195], v[122:125]
	v_mfma_f32_16x16x32_bf16 v[114:117], v[168:171], v[192:195], v[114:117]
	v_mfma_f32_16x16x32_bf16 v[106:109], v[160:163], v[200:203], v[106:109]
	v_mfma_f32_16x16x32_bf16 v[102:105], v[168:171], v[200:203], v[102:105]
	v_mfma_f32_16x16x32_bf16 v[90:93], v[160:163], v[208:211], v[90:93]
	v_mfma_f32_16x16x32_bf16 v[86:89], v[168:171], v[208:211], v[86:89]
	v_mfma_f32_16x16x32_bf16 v[74:77], v[160:163], v[216:219], v[74:77]
	v_mfma_f32_16x16x32_bf16 v[70:73], v[168:171], v[216:219], v[70:73]
	s_setprio 0
	s_setprio 1
	v_mfma_f32_16x16x32_bf16 v[126:129], v[172:175], v[188:191], v[126:129]
	v_mfma_f32_16x16x32_bf16 v[118:121], v[180:183], v[188:191], v[118:121]
	v_mfma_f32_16x16x32_bf16 v[110:113], v[172:175], v[196:199], v[110:113]
	v_mfma_f32_16x16x32_bf16 v[98:101], v[180:183], v[196:199], v[98:101]
	v_mfma_f32_16x16x32_bf16 v[94:97], v[172:175], v[204:207], v[94:97]
	v_mfma_f32_16x16x32_bf16 v[82:85], v[180:183], v[204:207], v[82:85]
	v_mfma_f32_16x16x32_bf16 v[78:81], v[172:175], v[212:215], v[78:81]
	v_mfma_f32_16x16x32_bf16 v[66:69], v[180:183], v[212:215], v[66:69]
	v_mfma_f32_16x16x32_bf16 v[126:129], v[176:179], v[192:195], v[126:129]
	v_mfma_f32_16x16x32_bf16 v[118:121], v[184:187], v[192:195], v[118:121]
	v_mfma_f32_16x16x32_bf16 v[110:113], v[176:179], v[200:203], v[110:113]
	v_mfma_f32_16x16x32_bf16 v[98:101], v[184:187], v[200:203], v[98:101]
	v_mfma_f32_16x16x32_bf16 v[94:97], v[176:179], v[208:211], v[94:97]
	v_mfma_f32_16x16x32_bf16 v[82:85], v[184:187], v[208:211], v[82:85]
	v_mfma_f32_16x16x32_bf16 v[78:81], v[176:179], v[216:219], v[78:81]
	v_mfma_f32_16x16x32_bf16 v[66:69], v[184:187], v[216:219], v[66:69]
	s_setprio 0
	s_barrier
	s_add_i32 s58, s47, s35
	v_lshl_add_u64 v[146:147], s[26:27], 0, v[134:135]
	s_mov_b32 m0, s58
	ds_read_b128 v[188:191], v151 offset:16384
	ds_read_b128 v[192:195], v151 offset:17408
	ds_read_b128 v[196:199], v151 offset:18432
	ds_read_b128 v[200:203], v151 offset:19456
	ds_read_b128 v[204:207], v151 offset:20480
	ds_read_b128 v[208:211], v151 offset:21504
	ds_read_b128 v[212:215], v151 offset:22528
	ds_read_b128 v[216:219], v151 offset:23552
	global_load_lds_dwordx4 v[146:147], off
	s_add_i32 m0, s58, 0x2000
	s_add_u32 s58, s26, 0x40000
	v_lshl_add_u64 v[220:221], s[26:27], 0, v[130:131]
	s_addc_u32 s59, s27, 0
	s_add_i32 s60, s48, s35
	global_load_lds_dwordx4 v[220:221], off
	v_lshl_add_u64 v[222:223], s[58:59], 0, v[134:135]
	s_mov_b32 m0, s60
	v_lshl_add_u64 v[224:225], s[28:29], 0, v[132:133]
	global_load_lds_dwordx4 v[222:223], off
	v_lshl_add_u64 v[222:223], s[58:59], 0, v[130:131]
	s_add_i32 m0, s60, 0x2000
	s_nop 0
	global_load_lds_dwordx4 v[222:223], off
	v_lshl_add_u64 v[222:223], s[28:29], 0, v[136:137]
	s_mov_b32 m0, s38
	s_nop 0
	global_load_lds_dwordx4 v[222:223], off
	s_mov_b32 m0, s39
	s_nop 0
	global_load_lds_dwordx4 v[224:225], off
	s_waitcnt vmcnt(8)
	s_waitcnt lgkmcnt(0)
	s_barrier
	s_setprio 1
	s_waitcnt lgkmcnt(0)
	v_mfma_f32_16x16x32_bf16 v[58:61], v[156:159], v[188:191], v[58:61]
	v_mfma_f32_16x16x32_bf16 v[54:57], v[164:167], v[188:191], v[54:57]
	v_mfma_f32_16x16x32_bf16 v[42:45], v[156:159], v[196:199], v[42:45]
	v_mfma_f32_16x16x32_bf16 v[38:41], v[164:167], v[196:199], v[38:41]
	v_mfma_f32_16x16x32_bf16 v[26:29], v[156:159], v[204:207], v[26:29]
	v_mfma_f32_16x16x32_bf16 v[22:25], v[164:167], v[204:207], v[22:25]
	v_mfma_f32_16x16x32_bf16 v[14:17], v[156:159], v[212:215], v[14:17]
	v_mfma_f32_16x16x32_bf16 v[6:9], v[164:167], v[212:215], v[6:9]
	v_mfma_f32_16x16x32_bf16 v[58:61], v[160:163], v[192:195], v[58:61]
	v_mfma_f32_16x16x32_bf16 v[54:57], v[168:171], v[192:195], v[54:57]
	v_mfma_f32_16x16x32_bf16 v[42:45], v[160:163], v[200:203], v[42:45]
	v_mfma_f32_16x16x32_bf16 v[38:41], v[168:171], v[200:203], v[38:41]
	v_mfma_f32_16x16x32_bf16 v[26:29], v[160:163], v[208:211], v[26:29]
	v_mfma_f32_16x16x32_bf16 v[22:25], v[168:171], v[208:211], v[22:25]
	v_mfma_f32_16x16x32_bf16 v[14:17], v[160:163], v[216:219], v[14:17]
	v_mfma_f32_16x16x32_bf16 v[6:9], v[168:171], v[216:219], v[6:9]
	s_setprio 0
	s_setprio 1
	v_mfma_f32_16x16x32_bf16 v[62:65], v[172:175], v[188:191], v[62:65]
	v_mfma_f32_16x16x32_bf16 v[50:53], v[180:183], v[188:191], v[50:53]
	v_mfma_f32_16x16x32_bf16 v[46:49], v[172:175], v[196:199], v[46:49]
	v_mfma_f32_16x16x32_bf16 v[34:37], v[180:183], v[196:199], v[34:37]
	v_mfma_f32_16x16x32_bf16 v[30:33], v[172:175], v[204:207], v[30:33]
	v_mfma_f32_16x16x32_bf16 v[18:21], v[180:183], v[204:207], v[18:21]
	v_mfma_f32_16x16x32_bf16 v[10:13], v[172:175], v[212:215], v[10:13]
	v_mfma_f32_16x16x32_bf16 v[2:5], v[180:183], v[212:215], v[2:5]
	v_mfma_f32_16x16x32_bf16 v[62:65], v[176:179], v[192:195], v[62:65]
	v_mfma_f32_16x16x32_bf16 v[50:53], v[184:187], v[192:195], v[50:53]
	v_mfma_f32_16x16x32_bf16 v[46:49], v[176:179], v[200:203], v[46:49]
	v_mfma_f32_16x16x32_bf16 v[34:37], v[184:187], v[200:203], v[34:37]
	v_mfma_f32_16x16x32_bf16 v[30:33], v[176:179], v[208:211], v[30:33]
	v_mfma_f32_16x16x32_bf16 v[18:21], v[184:187], v[208:211], v[18:21]
	v_mfma_f32_16x16x32_bf16 v[10:13], v[176:179], v[216:219], v[10:13]
	v_mfma_f32_16x16x32_bf16 v[2:5], v[184:187], v[216:219], v[2:5]
	s_setprio 0
	s_barrier
	ds_read_b128 v[156:159], v154
	ds_read_b128 v[160:163], v154 offset:1024
	ds_read_b128 v[164:167], v154 offset:2048
	ds_read_b128 v[168:171], v154 offset:3072
	ds_read_b128 v[172:175], v155
	ds_read_b128 v[176:179], v155 offset:1024
	ds_read_b128 v[180:183], v155 offset:2048
	ds_read_b128 v[184:187], v155 offset:3072
	s_add_u32 s28, s28, 0x40000
	s_addc_u32 s29, s29, 0
	s_mov_b32 m0, s40
	v_lshl_add_u64 v[226:227], s[28:29], 0, v[136:137]
	ds_read_b128 v[188:191], v151 offset:32768
	ds_read_b128 v[192:195], v151 offset:33792
	ds_read_b128 v[196:199], v151 offset:34816
	ds_read_b128 v[200:203], v151 offset:35840
	ds_read_b128 v[204:207], v151 offset:36864
	ds_read_b128 v[208:211], v151 offset:37888
	ds_read_b128 v[212:215], v151 offset:38912
	ds_read_b128 v[216:219], v151 offset:39936
	global_load_lds_dwordx4 v[226:227], off
	v_lshl_add_u64 v[226:227], s[28:29], 0, v[132:133]
	s_mov_b32 m0, s41
	s_nop 0
	global_load_lds_dwordx4 v[226:227], off
	s_cmp_lg_u32 s57, 12
	s_cbranch_scc1 .Lss_pf_skip_a
	v_lshl_add_u32 v244, s6, 8, v1
	v_ashrrev_i32_e32 v245, 31, v244
	v_lshlrev_b64 v[244:245], 6, v[244:245]
	v_lshl_add_u64 v[244:245], s[8:9], 0, v[244:245]
	global_load_dwordx4 v[228:231], v[244:245], off
	global_load_dwordx4 v[232:235], v[244:245], off offset:16
	global_load_dwordx4 v[236:239], v[244:245], off offset:32
	global_load_dwordx4 v[240:243], v[244:245], off offset:48
.Lss_pf_skip_a:
	s_waitcnt vmcnt(8)
	s_waitcnt lgkmcnt(0)
	s_barrier
	s_setprio 1
	s_waitcnt lgkmcnt(0)
	v_mfma_f32_16x16x32_bf16 v[122:125], v[156:159], v[188:191], v[122:125]
	v_mfma_f32_16x16x32_bf16 v[114:117], v[164:167], v[188:191], v[114:117]
	v_mfma_f32_16x16x32_bf16 v[106:109], v[156:159], v[196:199], v[106:109]
	v_mfma_f32_16x16x32_bf16 v[102:105], v[164:167], v[196:199], v[102:105]
	v_mfma_f32_16x16x32_bf16 v[90:93], v[156:159], v[204:207], v[90:93]
	v_mfma_f32_16x16x32_bf16 v[86:89], v[164:167], v[204:207], v[86:89]
	v_mfma_f32_16x16x32_bf16 v[74:77], v[156:159], v[212:215], v[74:77]
	v_mfma_f32_16x16x32_bf16 v[70:73], v[164:167], v[212:215], v[70:73]
	v_mfma_f32_16x16x32_bf16 v[122:125], v[160:163], v[192:195], v[122:125]
	v_mfma_f32_16x16x32_bf16 v[114:117], v[168:171], v[192:195], v[114:117]
	v_mfma_f32_16x16x32_bf16 v[106:109], v[160:163], v[200:203], v[106:109]
	v_mfma_f32_16x16x32_bf16 v[102:105], v[168:171], v[200:203], v[102:105]
	v_mfma_f32_16x16x32_bf16 v[90:93], v[160:163], v[208:211], v[90:93]
	v_mfma_f32_16x16x32_bf16 v[86:89], v[168:171], v[208:211], v[86:89]
	v_mfma_f32_16x16x32_bf16 v[74:77], v[160:163], v[216:219], v[74:77]
	v_mfma_f32_16x16x32_bf16 v[70:73], v[168:171], v[216:219], v[70:73]
	s_setprio 0
	s_setprio 1
	v_mfma_f32_16x16x32_bf16 v[126:129], v[172:175], v[188:191], v[126:129]
	v_mfma_f32_16x16x32_bf16 v[118:121], v[180:183], v[188:191], v[118:121]
	v_mfma_f32_16x16x32_bf16 v[110:113], v[172:175], v[196:199], v[110:113]
	v_mfma_f32_16x16x32_bf16 v[98:101], v[180:183], v[196:199], v[98:101]
	v_mfma_f32_16x16x32_bf16 v[94:97], v[172:175], v[204:207], v[94:97]
	v_mfma_f32_16x16x32_bf16 v[82:85], v[180:183], v[204:207], v[82:85]
	v_mfma_f32_16x16x32_bf16 v[78:81], v[172:175], v[212:215], v[78:81]
	v_mfma_f32_16x16x32_bf16 v[66:69], v[180:183], v[212:215], v[66:69]
	v_mfma_f32_16x16x32_bf16 v[126:129], v[176:179], v[192:195], v[126:129]
	v_mfma_f32_16x16x32_bf16 v[118:121], v[184:187], v[192:195], v[118:121]
	v_mfma_f32_16x16x32_bf16 v[110:113], v[176:179], v[200:203], v[110:113]
	v_mfma_f32_16x16x32_bf16 v[98:101], v[184:187], v[200:203], v[98:101]
	v_mfma_f32_16x16x32_bf16 v[94:97], v[176:179], v[208:211], v[94:97]
	v_mfma_f32_16x16x32_bf16 v[82:85], v[184:187], v[208:211], v[82:85]
	v_mfma_f32_16x16x32_bf16 v[78:81], v[176:179], v[216:219], v[78:81]
	v_mfma_f32_16x16x32_bf16 v[66:69], v[184:187], v[216:219], v[66:69]
	s_setprio 0
	s_barrier
	s_add_i32 s28, s51, s35
	v_lshl_add_u64 v[146:147], v[146:147], 0, s[12:13]
	s_mov_b32 m0, s28
	ds_read_b128 v[188:191], v151 offset:49152
	ds_read_b128 v[192:195], v151 offset:50176
	ds_read_b128 v[196:199], v151 offset:51200
	ds_read_b128 v[200:203], v151 offset:52224
	ds_read_b128 v[204:207], v151 offset:53248
	ds_read_b128 v[208:211], v151 offset:54272
	ds_read_b128 v[212:215], v151 offset:55296
	ds_read_b128 v[216:219], v151 offset:56320
	global_load_lds_dwordx4 v[146:147], off
	s_add_i32 m0, s28, 0x2000
	s_add_u32 s26, s26, 0x40080
	v_lshl_add_u64 v[146:147], v[220:221], 0, s[12:13]
	s_addc_u32 s27, s27, 0
	s_add_i32 s28, s52, s35
	global_load_lds_dwordx4 v[146:147], off
	v_lshl_add_u64 v[146:147], s[26:27], 0, v[134:135]
	s_mov_b32 m0, s28
	s_nop 0
	global_load_lds_dwordx4 v[146:147], off
	v_lshl_add_u64 v[146:147], s[26:27], 0, v[130:131]
	s_add_i32 m0, s28, 0x2000
	s_nop 0
	global_load_lds_dwordx4 v[146:147], off
	v_lshl_add_u64 v[146:147], v[222:223], 0, s[12:13]
	s_mov_b32 m0, s44
	s_nop 0
	global_load_lds_dwordx4 v[146:147], off
	v_lshl_add_u64 v[146:147], v[224:225], 0, s[12:13]
	s_mov_b32 m0, s45
	s_nop 0
	global_load_lds_dwordx4 v[146:147], off
	s_waitcnt vmcnt(8)
	s_waitcnt lgkmcnt(0)
	s_barrier
	s_setprio 1
	s_waitcnt lgkmcnt(0)
	v_mfma_f32_16x16x32_bf16 v[58:61], v[156:159], v[188:191], v[58:61]
	v_mfma_f32_16x16x32_bf16 v[54:57], v[164:167], v[188:191], v[54:57]
	v_mfma_f32_16x16x32_bf16 v[42:45], v[156:159], v[196:199], v[42:45]
	v_mfma_f32_16x16x32_bf16 v[38:41], v[164:167], v[196:199], v[38:41]
	v_mfma_f32_16x16x32_bf16 v[26:29], v[156:159], v[204:207], v[26:29]
	v_mfma_f32_16x16x32_bf16 v[22:25], v[164:167], v[204:207], v[22:25]
	v_mfma_f32_16x16x32_bf16 v[14:17], v[156:159], v[212:215], v[14:17]
	v_mfma_f32_16x16x32_bf16 v[6:9], v[164:167], v[212:215], v[6:9]
	v_mfma_f32_16x16x32_bf16 v[58:61], v[160:163], v[192:195], v[58:61]
	v_mfma_f32_16x16x32_bf16 v[54:57], v[168:171], v[192:195], v[54:57]
	v_mfma_f32_16x16x32_bf16 v[42:45], v[160:163], v[200:203], v[42:45]
	v_mfma_f32_16x16x32_bf16 v[38:41], v[168:171], v[200:203], v[38:41]
	v_mfma_f32_16x16x32_bf16 v[26:29], v[160:163], v[208:211], v[26:29]
	v_mfma_f32_16x16x32_bf16 v[22:25], v[168:171], v[208:211], v[22:25]
	v_mfma_f32_16x16x32_bf16 v[14:17], v[160:163], v[216:219], v[14:17]
	v_mfma_f32_16x16x32_bf16 v[6:9], v[168:171], v[216:219], v[6:9]
	s_setprio 0
	s_setprio 1
	v_mfma_f32_16x16x32_bf16 v[62:65], v[172:175], v[188:191], v[62:65]
	v_mfma_f32_16x16x32_bf16 v[50:53], v[180:183], v[188:191], v[50:53]
	v_mfma_f32_16x16x32_bf16 v[46:49], v[172:175], v[196:199], v[46:49]
	v_mfma_f32_16x16x32_bf16 v[34:37], v[180:183], v[196:199], v[34:37]
	v_mfma_f32_16x16x32_bf16 v[30:33], v[172:175], v[204:207], v[30:33]
	v_mfma_f32_16x16x32_bf16 v[18:21], v[180:183], v[204:207], v[18:21]
	v_mfma_f32_16x16x32_bf16 v[10:13], v[172:175], v[212:215], v[10:13]
	v_mfma_f32_16x16x32_bf16 v[2:5], v[180:183], v[212:215], v[2:5]
	v_mfma_f32_16x16x32_bf16 v[62:65], v[176:179], v[192:195], v[62:65]
	v_mfma_f32_16x16x32_bf16 v[50:53], v[184:187], v[192:195], v[50:53]
	v_mfma_f32_16x16x32_bf16 v[46:49], v[176:179], v[200:203], v[46:49]
	v_mfma_f32_16x16x32_bf16 v[34:37], v[184:187], v[200:203], v[34:37]
	v_mfma_f32_16x16x32_bf16 v[30:33], v[176:179], v[208:211], v[30:33]
	v_mfma_f32_16x16x32_bf16 v[18:21], v[184:187], v[208:211], v[18:21]
	v_mfma_f32_16x16x32_bf16 v[10:13], v[176:179], v[216:219], v[10:13]
	v_mfma_f32_16x16x32_bf16 v[2:5], v[184:187], v[216:219], v[2:5]
	s_setprio 0
	s_barrier
	s_add_i32 s57, s57, 2
	s_add_u32 s24, s24, 0x100
	s_addc_u32 s25, s25, 0
	s_add_u32 s55, s55, 0x100
	s_addc_u32 s56, s56, 0
	s_cmp_gt_u32 s57, 13
	s_cbranch_scc0 .LBB0_252
	s_and_b64 vcc, exec, s[14:15]
	s_cbranch_vccz .LBB0_255
	s_barrier
.LBB0_255:
	v_lshl_add_u32 v146, s6, 8, v1
	v_ashrrev_i32_e32 v147, 31, v146
	v_lshlrev_b64 v[156:157], 6, v[146:147]
	v_lshl_add_u64 v[168:169], s[8:9], 0, v[156:157]
	v_mov_b64_e32 v[208:209], v[168:169]
	s_movk_i32 s98, 0x2000
	s_mov_b32 s99, 0
	v_lshl_add_u64 v[210:211], v[208:209], 0, s[98:99]
	global_load_dwordx4 v[192:195], v[208:209], off offset:1024
	global_load_dwordx4 v[196:199], v[208:209], off offset:1040
	global_load_dwordx4 v[200:203], v[208:209], off offset:1056
	global_load_dwordx4 v[204:207], v[208:209], off offset:1072
	global_load_dwordx4 v[176:179], v[208:209], off offset:2048
	global_load_dwordx4 v[180:183], v[208:209], off offset:2064
	global_load_dwordx4 v[184:187], v[208:209], off offset:2080
	global_load_dwordx4 v[188:191], v[208:209], off offset:2096
	v_mov_b32_e32 v174, v126
	v_mov_b32_e32 v175, v122
	v_mov_b32_e32 v122, v127
	v_mov_b32_e32 v126, v128
	v_mov_b32_e32 v127, v124
	v_mov_b32_e32 v124, v129
	v_mov_b32_e32 v128, v118
	v_mov_b32_e32 v129, v114
	v_mov_b32_e32 v114, v119
	v_lshl_or_b32 v172, s7, 7, v148
	v_ashrrev_i32_e32 v173, 31, v172
	s_waitcnt vmcnt(8)
	v_mov_b32_e32 v156, v228
	v_mov_b32_e32 v157, v229
	v_mov_b32_e32 v158, v230
	v_mov_b32_e32 v159, v231
	v_mov_b32_e32 v160, v232
	v_mov_b32_e32 v161, v233
	v_mov_b32_e32 v162, v234
	v_mov_b32_e32 v163, v235
	v_mov_b32_e32 v164, v236
	v_mov_b32_e32 v165, v237
	v_mov_b32_e32 v166, v238
	v_mov_b32_e32 v167, v239
	v_mov_b32_e32 v168, v240
	v_mov_b32_e32 v169, v241
	v_mov_b32_e32 v170, v242
	v_mov_b32_e32 v171, v243
	v_mov_b32_e32 v118, v157
	v_mov_b32_e32 v119, v158
	v_mov_b32_e32 v157, v159
	v_mov_b32_e32 v158, v161
	v_mov_b32_e32 v159, v162
	v_mov_b32_e32 v161, v163
	v_pk_add_f32 v[118:119], v[118:119], v[156:157]
	v_pk_add_f32 v[156:157], v[158:159], v[160:161]
	v_pk_add_f32 v[118:119], v[118:119], v[118:119] op_sel:[0,1] op_sel_hi:[1,0]
	v_pk_add_f32 v[156:157], v[156:157], v[156:157] op_sel:[0,1] op_sel_hi:[1,0]
	v_add_f32_e32 v162, v164, v165
	v_add_f32_e32 v164, v166, v167
	v_mov_b32_e32 v163, v170
	v_mov_b32_e32 v165, v171
	v_mov_b32_e32 v119, v168
	v_mov_b32_e32 v157, v169
	v_pk_add_f32 v[158:159], v[162:163], v[164:165]
	v_pk_add_f32 v[118:119], v[118:119], v[156:157]
	s_nop 0
	v_pk_add_f32 v[118:119], v[118:119], v[158:159]
	s_nop 0
	v_add_f32_e32 v118, v118, v119
	v_fmamk_f32 v118, v118, 0x3a800000, v152
	v_mul_f32_e32 v119, 0x4f800000, v118
	v_cmp_gt_f32_e32 vcc, s49, v118
	s_nop 1
	v_cndmask_b32_e32 v147, v118, v119, vcc
	v_sqrt_f32_e32 v156, v147
	v_mov_b32_e32 v118, v120
	v_mov_b32_e32 v119, v116
	v_mov_b32_e32 v116, v121
	v_add_u32_e32 v120, -1, v156
	v_add_u32_e32 v121, 1, v156
	v_fma_f32 v157, -v120, v156, v147
	v_fma_f32 v158, -v121, v156, v147
	v_cmp_ge_f32_e64 s[6:7], 0, v157
	s_nop 1
	v_cndmask_b32_e64 v120, v156, v120, s[6:7]
	v_cmp_lt_f32_e64 s[6:7], 0, v158
	s_nop 1
	v_cndmask_b32_e64 v120, v120, v121, s[6:7]
	v_mul_f32_e32 v121, 0x37800000, v120
	v_cndmask_b32_e32 v120, v120, v121, vcc
	v_cmp_class_f32_e32 vcc, v147, v153
	s_nop 1
	v_cndmask_b32_e32 v120, v120, v147, vcc
	v_div_scale_f32 v121, s[6:7], v120, v120, 1.0
	v_rcp_f32_e32 v147, v121
	v_div_scale_f32 v156, vcc, 1.0, v120, 1.0
	v_fma_f32 v157, -v121, v147, 1.0
	v_fmac_f32_e32 v147, v157, v147
	v_mul_f32_e32 v157, v156, v147
	v_fma_f32 v158, -v121, v157, v156
	v_fmac_f32_e32 v157, v158, v147
	v_fma_f32 v121, -v121, v157, v156
	v_div_fmas_f32 v121, v121, v147, v157
	v_div_fixup_f32 v120, v121, v120, 1.0
	v_pk_mul_f32 v[156:157], v[174:175], v[120:121] op_sel_hi:[1,0]
	v_pk_mul_f32 v[122:123], v[122:123], v[120:121] op_sel_hi:[1,0]
	v_pk_mul_f32 v[114:115], v[114:115], v[120:121] op_sel_hi:[1,0]
	v_pk_mul_f32 v[118:119], v[118:119], v[120:121] op_sel_hi:[1,0]
	v_pk_mul_f32 v[126:127], v[126:127], v[120:121] op_sel_hi:[1,0]
	v_pk_mul_f32 v[124:125], v[124:125], v[120:121] op_sel_hi:[1,0]
	v_pk_mul_f32 v[128:129], v[128:129], v[120:121] op_sel_hi:[1,0]
	v_pk_mul_f32 v[116:117], v[116:117], v[120:121] op_sel_hi:[1,0]
	v_mul_f32_e32 v120, 0xbfb8aa3b, v157
	v_mul_f32_e32 v121, 0xbfb8aa3b, v123
	v_mul_f32_e32 v160, 0xbfb8aa3b, v115
	v_mul_f32_e32 v161, 0xbfb8aa3b, v119
	v_mul_f32_e32 v147, 0xbfb8aa3b, v127
	v_mul_f32_e32 v158, 0xbfb8aa3b, v125
	v_mul_f32_e32 v159, 0xbfb8aa3b, v129
	v_mul_f32_e32 v162, 0xbfb8aa3b, v117
	v_exp_f32_e32 v120, v120
	v_exp_f32_e32 v121, v121
	v_exp_f32_e32 v160, v160
	v_exp_f32_e32 v161, v161
	v_exp_f32_e32 v147, v147
	v_exp_f32_e32 v158, v158
	v_exp_f32_e32 v159, v159
	v_exp_f32_e32 v162, v162
	v_add_f32_e32 v120, 1.0, v120
	v_add_f32_e32 v121, 1.0, v121
	v_add_f32_e32 v160, 1.0, v160
	v_add_f32_e32 v161, 1.0, v161
	v_add_f32_e32 v147, 1.0, v147
	v_add_f32_e32 v158, 1.0, v158
	v_add_f32_e32 v159, 1.0, v159
	v_add_f32_e32 v162, 1.0, v162
	v_rcp_f32_e32 v120, v120
	v_rcp_f32_e32 v121, v121
	v_rcp_f32_e32 v160, v160
	v_rcp_f32_e32 v161, v161
	v_rcp_f32_e32 v147, v147
	v_rcp_f32_e32 v158, v158
	v_rcp_f32_e32 v159, v159
	v_rcp_f32_e32 v162, v162
	v_mul_f32_e32 v120, v157, v120
	v_mul_f32_e32 v121, v123, v121
	v_mul_f32_e32 v115, v115, v160
	v_mul_f32_e32 v119, v119, v161
	v_mul_f32_e32 v123, v127, v147
	v_mul_f32_e32 v125, v125, v158
	v_mul_f32_e32 v127, v129, v159
	v_mul_f32_e32 v117, v117, v162
	v_mul_f32_e32 v120, v156, v120
	v_mul_f32_e32 v121, v122, v121
	v_mul_f32_e32 v114, v114, v115
	v_mul_f32_e32 v115, v118, v119
	v_mul_f32_e32 v122, v126, v123
	v_mul_f32_e32 v123, v124, v125
	v_mul_f32_e32 v124, v128, v127
	v_mul_f32_e32 v116, v116, v117
	v_cvt_pk_bf16_f32 v118, v120, v121
	v_cvt_pk_bf16_f32 v119, v122, v123
	v_cvt_pk_bf16_f32 v120, v124, v114
	v_cvt_pk_bf16_f32 v121, v115, v116
	v_mov_b64_e32 v[114:115], s[10:11]
	v_mad_i64_i32 v[122:123], s[6:7], v146, s50, v[114:115]
	v_lshlrev_b64 v[116:117], 1, v[172:173]
	v_lshl_add_u64 v[122:123], v[122:123], 0, v[116:117]
	global_store_dwordx4 v[122:123], v[118:121], off nt
	s_nop 1
	v_or_b32_e32 v118, 16, v146
	v_ashrrev_i32_e32 v119, 31, v118
	v_lshlrev_b64 v[120:121], 6, v[118:119]
	v_lshl_add_u64 v[128:129], s[8:9], 0, v[120:121]
	s_waitcnt vmcnt(5)
	v_mov_b32_e32 v120, v192
	v_mov_b32_e32 v121, v193
	v_mov_b32_e32 v122, v194
	v_mov_b32_e32 v123, v195
	v_mov_b32_e32 v124, v196
	v_mov_b32_e32 v125, v197
	v_mov_b32_e32 v126, v198
	v_mov_b32_e32 v127, v199
	v_mov_b32_e32 v156, v200
	v_mov_b32_e32 v157, v201
	v_mov_b32_e32 v158, v202
	v_mov_b32_e32 v159, v203
	v_mov_b32_e32 v160, v204
	v_mov_b32_e32 v161, v205
	v_mov_b32_e32 v162, v206
	v_mov_b32_e32 v163, v207
	global_load_dwordx4 v[192:195], v[208:209], off offset:3072
	global_load_dwordx4 v[196:199], v[208:209], off offset:3088
	global_load_dwordx4 v[200:203], v[208:209], off offset:3104
	global_load_dwordx4 v[204:207], v[208:209], off offset:3120
	v_mov_b32_e32 v128, v110
	v_mov_b32_e32 v110, v112
	v_mov_b32_e32 v112, v98
	v_mov_b32_e32 v129, v106
	v_mov_b32_e32 v106, v111
	v_mov_b32_e32 v111, v108
	v_mov_b32_e32 v108, v113
	v_mov_b32_e32 v113, v102
	v_mov_b32_e32 v164, v121
	v_mov_b32_e32 v165, v122
	v_mov_b32_e32 v121, v123
	v_mov_b32_e32 v122, v125
	v_mov_b32_e32 v123, v126
	v_mov_b32_e32 v125, v127
	v_pk_add_f32 v[120:121], v[164:165], v[120:121]
	v_pk_add_f32 v[122:123], v[122:123], v[124:125]
	v_pk_add_f32 v[120:121], v[120:121], v[120:121] op_sel:[0,1] op_sel_hi:[1,0]
	v_pk_add_f32 v[122:123], v[122:123], v[122:123] op_sel:[0,1] op_sel_hi:[1,0]
	v_add_f32_e32 v126, v156, v157
	v_add_f32_e32 v156, v158, v159
	v_mov_b32_e32 v127, v162
	v_mov_b32_e32 v157, v163
	v_mov_b32_e32 v121, v160
	v_mov_b32_e32 v123, v161
	v_pk_add_f32 v[124:125], v[126:127], v[156:157]
	v_pk_add_f32 v[120:121], v[120:121], v[122:123]
	s_nop 0
	v_pk_add_f32 v[120:121], v[120:121], v[124:125]
	s_nop 0
	v_add_f32_e32 v98, v120, v121
	v_fmamk_f32 v98, v98, 0x3a800000, v152
	v_mul_f32_e32 v102, 0x4f800000, v98
	v_cmp_gt_f32_e32 vcc, s49, v98
	s_nop 1
	v_cndmask_b32_e32 v119, v98, v102, vcc
	v_sqrt_f32_e32 v120, v119
	v_mov_b32_e32 v98, v100
	v_mov_b32_e32 v102, v99
	v_mov_b32_e32 v99, v104
	v_add_u32_e32 v100, -1, v120
	v_add_u32_e32 v104, 1, v120
	v_fma_f32 v121, -v100, v120, v119
	v_fma_f32 v122, -v104, v120, v119
	v_cmp_ge_f32_e64 s[6:7], 0, v121
	s_nop 1
	v_cndmask_b32_e64 v100, v120, v100, s[6:7]
	v_cmp_lt_f32_e64 s[6:7], 0, v122
	s_nop 1
	v_cndmask_b32_e64 v100, v100, v104, s[6:7]
	v_mul_f32_e32 v104, 0x37800000, v100
	v_cndmask_b32_e32 v100, v100, v104, vcc
	v_cmp_class_f32_e32 vcc, v119, v153
	v_mov_b32_e32 v104, v101
	s_nop 0
	v_cndmask_b32_e32 v100, v100, v119, vcc
	v_div_scale_f32 v119, s[6:7], v100, v100, 1.0
	v_rcp_f32_e32 v120, v119
	v_div_scale_f32 v101, vcc, 1.0, v100, 1.0
	v_fma_f32 v121, -v119, v120, 1.0
	v_fmac_f32_e32 v120, v121, v120
	v_mul_f32_e32 v121, v101, v120
	v_fma_f32 v122, -v119, v121, v101
	v_fmac_f32_e32 v121, v122, v120
	v_fma_f32 v101, -v119, v121, v101
	v_div_fmas_f32 v101, v101, v120, v121
	v_div_fixup_f32 v100, v101, v100, 1.0
	v_pk_mul_f32 v[106:107], v[106:107], v[100:101] op_sel_hi:[1,0]
	v_pk_mul_f32 v[110:111], v[110:111], v[100:101] op_sel_hi:[1,0]
	v_pk_mul_f32 v[108:109], v[108:109], v[100:101] op_sel_hi:[1,0]
	v_pk_mul_f32 v[120:121], v[128:129], v[100:101] op_sel_hi:[1,0]
	v_pk_mul_f32 v[112:113], v[112:113], v[100:101] op_sel_hi:[1,0]
	v_pk_mul_f32 v[102:103], v[102:103], v[100:101] op_sel_hi:[1,0]
	v_pk_mul_f32 v[98:99], v[98:99], v[100:101] op_sel_hi:[1,0]
	v_pk_mul_f32 v[100:101], v[104:105], v[100:101] op_sel_hi:[1,0]
	v_mul_f32_e32 v105, 0xbfb8aa3b, v107
	v_mul_f32_e32 v119, 0xbfb8aa3b, v111
	v_mul_f32_e32 v122, 0xbfb8aa3b, v109
	v_exp_f32_e32 v105, v105
	v_exp_f32_e32 v119, v119
	v_exp_f32_e32 v122, v122
	v_mul_f32_e32 v124, 0xbfb8aa3b, v103
	v_mul_f32_e32 v125, 0xbfb8aa3b, v99
	v_mul_f32_e32 v126, 0xbfb8aa3b, v101
	v_exp_f32_e32 v124, v124
	v_exp_f32_e32 v125, v125
	v_add_f32_e32 v105, 1.0, v105
	v_add_f32_e32 v119, 1.0, v119
	v_add_f32_e32 v122, 1.0, v122
	v_mul_f32_e32 v104, 0xbfb8aa3b, v121
	v_mul_f32_e32 v123, 0xbfb8aa3b, v113
	v_exp_f32_e32 v126, v126
	v_rcp_f32_e32 v105, v105
	v_rcp_f32_e32 v119, v119
	v_rcp_f32_e32 v122, v122
	v_exp_f32_e32 v104, v104
	v_exp_f32_e32 v123, v123
	v_add_f32_e32 v124, 1.0, v124
	v_add_f32_e32 v125, 1.0, v125
	v_add_f32_e32 v126, 1.0, v126
	v_rcp_f32_e32 v124, v124
	v_rcp_f32_e32 v125, v125
	v_mul_f32_e32 v105, v107, v105
	v_mul_f32_e32 v107, v111, v119
	v_mul_f32_e32 v109, v109, v122
	v_add_f32_e32 v104, 1.0, v104
	v_add_f32_e32 v123, 1.0, v123
	v_mul_f32_e32 v105, v106, v105
	v_mul_f32_e32 v106, v110, v107
	v_mul_f32_e32 v107, v108, v109
	v_rcp_f32_e32 v109, v126
	v_rcp_f32_e32 v104, v104
	v_rcp_f32_e32 v123, v123
	v_mul_f32_e32 v103, v103, v124
	v_mul_f32_e32 v99, v99, v125
	v_mul_f32_e32 v102, v102, v103
	v_mul_f32_e32 v103, v98, v99
	v_mul_f32_e32 v98, v101, v109
	v_mul_f32_e32 v104, v121, v104
	v_mul_f32_e32 v111, v113, v123
	v_mul_f32_e32 v101, v100, v98
	v_mul_f32_e32 v104, v120, v104
	v_mul_f32_e32 v108, v112, v111
	v_cvt_pk_bf16_f32 v98, v104, v105
	v_cvt_pk_bf16_f32 v99, v106, v107
	v_cvt_pk_bf16_f32 v100, v108, v102
	v_cvt_pk_bf16_f32 v101, v103, v101
	v_mad_i64_i32 v[102:103], s[6:7], v118, s50, v[114:115]
	v_lshl_add_u64 v[102:103], v[102:103], 0, v[116:117]
	global_store_dwordx4 v[102:103], v[98:101], off nt
	s_nop 1
	v_or_b32_e32 v98, 32, v146
	v_ashrrev_i32_e32 v99, 31, v98
	v_lshlrev_b64 v[100:101], 6, v[98:99]
	v_lshl_add_u64 v[112:113], s[8:9], 0, v[100:101]
	s_waitcnt vmcnt(6)
	v_mov_b32_e32 v100, v176
	v_mov_b32_e32 v101, v177
	v_mov_b32_e32 v102, v178
	v_mov_b32_e32 v103, v179
	v_mov_b32_e32 v104, v180
	v_mov_b32_e32 v105, v181
	v_mov_b32_e32 v106, v182
	v_mov_b32_e32 v107, v183
	v_mov_b32_e32 v108, v184
	v_mov_b32_e32 v109, v185
	v_mov_b32_e32 v110, v186
	v_mov_b32_e32 v111, v187
	v_mov_b32_e32 v118, v188
	v_mov_b32_e32 v119, v189
	v_mov_b32_e32 v120, v190
	v_mov_b32_e32 v121, v191
	global_load_dwordx4 v[176:179], v[210:211], off
	global_load_dwordx4 v[180:183], v[210:211], off offset:16
	global_load_dwordx4 v[184:187], v[210:211], off offset:32
	global_load_dwordx4 v[188:191], v[210:211], off offset:48
	v_mov_b32_e32 v112, v94
	v_mov_b32_e32 v94, v96
	v_mov_b32_e32 v96, v82
	v_mov_b32_e32 v113, v90
	v_mov_b32_e32 v90, v95
	v_mov_b32_e32 v95, v92
	v_mov_b32_e32 v92, v97
	v_mov_b32_e32 v97, v86
	v_mov_b32_e32 v122, v101
	v_mov_b32_e32 v123, v102
	v_mov_b32_e32 v101, v103
	v_mov_b32_e32 v102, v105
	v_mov_b32_e32 v103, v106
	v_mov_b32_e32 v105, v107
	v_pk_add_f32 v[100:101], v[122:123], v[100:101]
	v_pk_add_f32 v[102:103], v[102:103], v[104:105]
	v_pk_add_f32 v[100:101], v[100:101], v[100:101] op_sel:[0,1] op_sel_hi:[1,0]
	v_pk_add_f32 v[102:103], v[102:103], v[102:103] op_sel:[0,1] op_sel_hi:[1,0]
	v_add_f32_e32 v106, v108, v109
	v_add_f32_e32 v108, v110, v111
	v_mov_b32_e32 v107, v120
	v_mov_b32_e32 v109, v121
	v_mov_b32_e32 v101, v118
	v_mov_b32_e32 v103, v119
	v_pk_add_f32 v[104:105], v[106:107], v[108:109]
	v_pk_add_f32 v[100:101], v[100:101], v[102:103]
	s_nop 0
	v_pk_add_f32 v[100:101], v[100:101], v[104:105]
	s_nop 0
	v_add_f32_e32 v82, v100, v101
	v_fmamk_f32 v82, v82, 0x3a800000, v152
	v_mul_f32_e32 v86, 0x4f800000, v82
	v_cmp_gt_f32_e32 vcc, s49, v82
	s_nop 1
	v_cndmask_b32_e32 v99, v82, v86, vcc
	v_sqrt_f32_e32 v100, v99
	v_mov_b32_e32 v82, v84
	v_mov_b32_e32 v86, v83
	v_mov_b32_e32 v83, v88
	v_add_u32_e32 v84, -1, v100
	v_add_u32_e32 v88, 1, v100
	v_fma_f32 v101, -v84, v100, v99
	v_fma_f32 v102, -v88, v100, v99
	v_cmp_ge_f32_e64 s[6:7], 0, v101
	s_nop 1
	v_cndmask_b32_e64 v84, v100, v84, s[6:7]
	v_cmp_lt_f32_e64 s[6:7], 0, v102
	s_nop 1
	v_cndmask_b32_e64 v84, v84, v88, s[6:7]
	v_mul_f32_e32 v88, 0x37800000, v84
	v_cndmask_b32_e32 v84, v84, v88, vcc
	v_cmp_class_f32_e32 vcc, v99, v153
	v_mov_b32_e32 v88, v85
	s_nop 0
	v_cndmask_b32_e32 v84, v84, v99, vcc
	v_div_scale_f32 v99, s[6:7], v84, v84, 1.0
	v_rcp_f32_e32 v100, v99
	v_div_scale_f32 v85, vcc, 1.0, v84, 1.0
	v_fma_f32 v101, -v99, v100, 1.0
	v_fmac_f32_e32 v100, v101, v100
	v_mul_f32_e32 v101, v85, v100
	v_fma_f32 v102, -v99, v101, v85
	v_fmac_f32_e32 v101, v102, v100
	v_fma_f32 v85, -v99, v101, v85
	v_div_fmas_f32 v85, v85, v100, v101
	v_div_fixup_f32 v84, v85, v84, 1.0
	v_pk_mul_f32 v[90:91], v[90:91], v[84:85] op_sel_hi:[1,0]
	v_pk_mul_f32 v[94:95], v[94:95], v[84:85] op_sel_hi:[1,0]
	v_pk_mul_f32 v[92:93], v[92:93], v[84:85] op_sel_hi:[1,0]
	v_pk_mul_f32 v[100:101], v[112:113], v[84:85] op_sel_hi:[1,0]
	v_pk_mul_f32 v[96:97], v[96:97], v[84:85] op_sel_hi:[1,0]
	v_pk_mul_f32 v[86:87], v[86:87], v[84:85] op_sel_hi:[1,0]
	v_pk_mul_f32 v[82:83], v[82:83], v[84:85] op_sel_hi:[1,0]
	v_pk_mul_f32 v[84:85], v[88:89], v[84:85] op_sel_hi:[1,0]
	v_mul_f32_e32 v89, 0xbfb8aa3b, v91
	v_mul_f32_e32 v99, 0xbfb8aa3b, v95
	v_mul_f32_e32 v102, 0xbfb8aa3b, v93
	v_exp_f32_e32 v89, v89
	v_exp_f32_e32 v99, v99
	v_exp_f32_e32 v102, v102
	v_mul_f32_e32 v104, 0xbfb8aa3b, v87
	v_add_f32_e32 v89, 1.0, v89
	v_add_f32_e32 v99, 1.0, v99
	v_add_f32_e32 v102, 1.0, v102
	v_rcp_f32_e32 v89, v89
	v_rcp_f32_e32 v99, v99
	v_rcp_f32_e32 v102, v102
	v_mul_f32_e32 v105, 0xbfb8aa3b, v83
	v_mul_f32_e32 v89, v91, v89
	v_mul_f32_e32 v91, v95, v99
	v_mul_f32_e32 v93, v93, v102
	v_exp_f32_e32 v104, v104
	v_exp_f32_e32 v105, v105
	v_mul_f32_e32 v89, v90, v89
	v_mul_f32_e32 v90, v94, v91
	v_mul_f32_e32 v91, v92, v93
	v_mul_f32_e32 v93, 0xbfb8aa3b, v85
	v_mul_f32_e32 v88, 0xbfb8aa3b, v101
	v_mul_f32_e32 v103, 0xbfb8aa3b, v97
	v_exp_f32_e32 v93, v93
	v_exp_f32_e32 v88, v88
	v_exp_f32_e32 v103, v103
	v_add_f32_e32 v104, 1.0, v104
	v_add_f32_e32 v94, 1.0, v105
	v_rcp_f32_e32 v104, v104
	v_rcp_f32_e32 v94, v94
	v_add_f32_e32 v93, 1.0, v93
	v_add_f32_e32 v88, 1.0, v88
	v_add_f32_e32 v103, 1.0, v103
	v_rcp_f32_e32 v93, v93
	v_rcp_f32_e32 v88, v88
	v_rcp_f32_e32 v103, v103
	v_mul_f32_e32 v87, v87, v104
	v_mul_f32_e32 v83, v83, v94
	v_mul_f32_e32 v86, v86, v87
	v_mul_f32_e32 v87, v82, v83
	v_mul_f32_e32 v82, v85, v93
	v_mul_f32_e32 v88, v101, v88
	v_mul_f32_e32 v95, v97, v103
	v_mul_f32_e32 v85, v84, v82
	v_mul_f32_e32 v88, v100, v88
	v_mul_f32_e32 v92, v96, v95
	v_cvt_pk_bf16_f32 v82, v88, v89
	v_cvt_pk_bf16_f32 v83, v90, v91
	v_cvt_pk_bf16_f32 v84, v92, v86
	v_cvt_pk_bf16_f32 v85, v87, v85
	v_mad_i64_i32 v[86:87], s[6:7], v98, s50, v[114:115]
	v_lshl_add_u64 v[86:87], v[86:87], 0, v[116:117]
	global_store_dwordx4 v[86:87], v[82:85], off nt
	v_mov_b32_e32 v100, v78
	v_mov_b32_e32 v101, v74
	v_or_b32_e32 v82, 48, v146
	v_ashrrev_i32_e32 v83, 31, v82
	v_lshlrev_b64 v[84:85], 6, v[82:83]
	v_lshl_add_u64 v[96:97], s[8:9], 0, v[84:85]
	s_waitcnt vmcnt(6)
	v_mov_b32_e32 v84, v192
	v_mov_b32_e32 v85, v193
	v_mov_b32_e32 v86, v194
	v_mov_b32_e32 v87, v195
	v_mov_b32_e32 v88, v196
	v_mov_b32_e32 v89, v197
	v_mov_b32_e32 v90, v198
	v_mov_b32_e32 v91, v199
	v_mov_b32_e32 v92, v200
	v_mov_b32_e32 v93, v201
	v_mov_b32_e32 v94, v202
	v_mov_b32_e32 v95, v203
	v_mov_b32_e32 v96, v204
	v_mov_b32_e32 v97, v205
	v_mov_b32_e32 v98, v206
	v_mov_b32_e32 v99, v207
	global_load_dwordx4 v[192:195], v[210:211], off offset:1024
	global_load_dwordx4 v[196:199], v[210:211], off offset:1040
	global_load_dwordx4 v[200:203], v[210:211], off offset:1056
	global_load_dwordx4 v[204:207], v[210:211], off offset:1072
	v_mov_b32_e32 v74, v79
	v_mov_b32_e32 v78, v80
	v_mov_b32_e32 v79, v76
	v_mov_b32_e32 v76, v81
	v_mov_b32_e32 v80, v85
	v_mov_b32_e32 v81, v86
	v_mov_b32_e32 v85, v87
	v_mov_b32_e32 v86, v89
	v_mov_b32_e32 v87, v90
	v_mov_b32_e32 v89, v91
	v_pk_add_f32 v[80:81], v[80:81], v[84:85]
	v_pk_add_f32 v[84:85], v[86:87], v[88:89]
	v_pk_add_f32 v[80:81], v[80:81], v[80:81] op_sel:[0,1] op_sel_hi:[1,0]
	v_pk_add_f32 v[84:85], v[84:85], v[84:85] op_sel:[0,1] op_sel_hi:[1,0]
	v_add_f32_e32 v90, v92, v93
	v_add_f32_e32 v92, v94, v95
	v_mov_b32_e32 v91, v98
	v_mov_b32_e32 v93, v99
	v_mov_b32_e32 v81, v96
	v_mov_b32_e32 v85, v97
	v_pk_add_f32 v[86:87], v[90:91], v[92:93]
	v_pk_add_f32 v[80:81], v[80:81], v[84:85]
	s_nop 0
	v_pk_add_f32 v[80:81], v[80:81], v[86:87]
	s_nop 0
	v_add_f32_e32 v80, v80, v81
	v_fmamk_f32 v80, v80, 0x3a800000, v152
	v_mul_f32_e32 v81, 0x4f800000, v80
	v_cmp_gt_f32_e32 vcc, s49, v80
	s_nop 1
	v_cndmask_b32_e32 v83, v80, v81, vcc
	v_sqrt_f32_e32 v84, v83
	v_mov_b32_e32 v80, v66
	v_mov_b32_e32 v81, v70
	v_mov_b32_e32 v70, v67
	v_add_u32_e32 v66, -1, v84
	v_add_u32_e32 v67, 1, v84
	v_fma_f32 v85, -v66, v84, v83
	v_fma_f32 v86, -v67, v84, v83
	v_cmp_ge_f32_e64 s[6:7], 0, v85
	s_nop 1
	v_cndmask_b32_e64 v66, v84, v66, s[6:7]
	v_cmp_lt_f32_e64 s[6:7], 0, v86
	s_nop 1
	v_cndmask_b32_e64 v66, v66, v67, s[6:7]
	v_mul_f32_e32 v67, 0x37800000, v66
	v_cndmask_b32_e32 v66, v66, v67, vcc
	v_cmp_class_f32_e32 vcc, v83, v153
	s_nop 1
	v_cndmask_b32_e32 v67, v66, v83, vcc
	v_div_scale_f32 v83, s[6:7], v67, v67, 1.0
	v_rcp_f32_e32 v84, v83
	v_mov_b32_e32 v66, v68
	v_div_scale_f32 v68, vcc, 1.0, v67, 1.0
	v_fma_f32 v85, -v83, v84, 1.0
	v_fmac_f32_e32 v84, v85, v84
	v_mul_f32_e32 v85, v68, v84
	v_fma_f32 v86, -v83, v85, v68
	v_fmac_f32_e32 v85, v86, v84
	v_fma_f32 v68, -v83, v85, v68
	v_div_fmas_f32 v68, v68, v84, v85
	v_div_fixup_f32 v68, v68, v67, 1.0
	v_pk_mul_f32 v[84:85], v[100:101], v[68:69] op_sel_hi:[1,0]
	v_pk_mul_f32 v[74:75], v[74:75], v[68:69] op_sel_hi:[1,0]
	v_mul_f32_e32 v67, 0xbfb8aa3b, v85
	v_mul_f32_e32 v83, 0xbfb8aa3b, v75
	v_exp_f32_e32 v67, v67
	v_pk_mul_f32 v[78:79], v[78:79], v[68:69] op_sel_hi:[1,0]
	v_exp_f32_e32 v83, v83
	v_mul_f32_e32 v86, 0xbfb8aa3b, v79
	v_exp_f32_e32 v86, v86
	v_add_f32_e32 v67, 1.0, v67
	v_add_f32_e32 v83, 1.0, v83
	v_rcp_f32_e32 v67, v67
	v_rcp_f32_e32 v83, v83
	v_add_f32_e32 v86, 1.0, v86
	v_rcp_f32_e32 v86, v86
	v_mul_f32_e32 v67, v85, v67
	v_mul_f32_e32 v75, v75, v83
	v_mul_f32_e32 v83, v84, v67
	v_mov_b32_e32 v67, v72
	v_pk_mul_f32 v[66:67], v[66:67], v[68:69] op_sel_hi:[1,0]
	v_mul_f32_e32 v79, v79, v86
	v_mul_f32_e32 v72, 0xbfb8aa3b, v67
	v_pk_mul_f32 v[70:71], v[70:71], v[68:69] op_sel_hi:[1,0]
	v_mul_f32_e32 v74, v74, v75
	v_mul_f32_e32 v75, v78, v79
	v_exp_f32_e32 v78, v72
	v_mov_b32_e32 v72, v69
	v_pk_mul_f32 v[76:77], v[76:77], v[68:69] op_sel_hi:[1,0]
	v_pk_mul_f32 v[80:81], v[80:81], v[68:69] op_sel_hi:[1,0]
	v_mul_f32_e32 v89, 0xbfb8aa3b, v71
	v_pk_mul_f32 v[68:69], v[72:73], v[68:69] op_sel_hi:[1,0]
	v_exp_f32_e32 v89, v89
	v_mul_f32_e32 v72, 0xbfb8aa3b, v69
	v_mul_f32_e32 v87, 0xbfb8aa3b, v77
	v_mul_f32_e32 v88, 0xbfb8aa3b, v81
	v_exp_f32_e32 v72, v72
	v_exp_f32_e32 v87, v87
	v_exp_f32_e32 v88, v88
	v_add_f32_e32 v89, 1.0, v89
	v_add_f32_e32 v73, 1.0, v78
	v_rcp_f32_e32 v89, v89
	v_rcp_f32_e32 v73, v73
	v_add_f32_e32 v72, 1.0, v72
	v_add_f32_e32 v87, 1.0, v87
	v_add_f32_e32 v88, 1.0, v88
	v_rcp_f32_e32 v72, v72
	v_rcp_f32_e32 v87, v87
	v_rcp_f32_e32 v88, v88
	v_mul_f32_e32 v71, v71, v89
	v_mul_f32_e32 v67, v67, v73
	v_mul_f32_e32 v70, v70, v71
	v_mul_f32_e32 v71, v66, v67
	v_mul_f32_e32 v66, v69, v72
	v_mul_f32_e32 v77, v77, v87
	v_mul_f32_e32 v81, v81, v88
	v_mul_f32_e32 v69, v68, v66
	v_mul_f32_e32 v76, v76, v77
	v_mul_f32_e32 v77, v80, v81
	v_cvt_pk_bf16_f32 v66, v83, v74
	v_cvt_pk_bf16_f32 v67, v75, v76
	v_cvt_pk_bf16_f32 v68, v77, v70
	v_cvt_pk_bf16_f32 v69, v71, v69
	v_mad_i64_i32 v[70:71], s[6:7], v82, s50, v[114:115]
	v_lshl_add_u64 v[70:71], v[70:71], 0, v[116:117]
	global_store_dwordx4 v[70:71], v[66:69], off nt
	v_mov_b32_e32 v85, v58
	v_mov_b32_e32 v58, v63
	v_add_u32_e32 v66, 0x80, v146
	v_ashrrev_i32_e32 v67, 31, v66
	v_lshlrev_b64 v[68:69], 6, v[66:67]
	v_lshl_add_u64 v[80:81], s[8:9], 0, v[68:69]
	s_waitcnt vmcnt(6)
	v_mov_b32_e32 v68, v176
	v_mov_b32_e32 v69, v177
	v_mov_b32_e32 v70, v178
	v_mov_b32_e32 v71, v179
	v_mov_b32_e32 v72, v180
	v_mov_b32_e32 v73, v181
	v_mov_b32_e32 v74, v182
	v_mov_b32_e32 v75, v183
	v_mov_b32_e32 v76, v184
	v_mov_b32_e32 v77, v185
	v_mov_b32_e32 v78, v186
	v_mov_b32_e32 v79, v187
	v_mov_b32_e32 v80, v188
	v_mov_b32_e32 v81, v189
	v_mov_b32_e32 v82, v190
	v_mov_b32_e32 v83, v191
	global_load_dwordx4 v[176:179], v[210:211], off offset:2048
	global_load_dwordx4 v[180:183], v[210:211], off offset:2064
	global_load_dwordx4 v[184:187], v[210:211], off offset:2080
	global_load_dwordx4 v[188:191], v[210:211], off offset:2096
	v_mov_b32_e32 v63, v60
	v_mov_b32_e32 v84, v62
	v_mov_b32_e32 v62, v64
	v_mov_b32_e32 v86, v69
	v_mov_b32_e32 v87, v70
	v_mov_b32_e32 v69, v71
	v_mov_b32_e32 v70, v73
	v_mov_b32_e32 v71, v74
	v_mov_b32_e32 v73, v75
	v_pk_add_f32 v[68:69], v[86:87], v[68:69]
	v_pk_add_f32 v[70:71], v[70:71], v[72:73]
	v_pk_add_f32 v[68:69], v[68:69], v[68:69] op_sel:[0,1] op_sel_hi:[1,0]
	v_pk_add_f32 v[70:71], v[70:71], v[70:71] op_sel:[0,1] op_sel_hi:[1,0]
	v_add_f32_e32 v74, v76, v77
	v_add_f32_e32 v76, v78, v79
	v_mov_b32_e32 v75, v82
	v_mov_b32_e32 v77, v83
	v_mov_b32_e32 v69, v80
	v_mov_b32_e32 v71, v81
	v_pk_add_f32 v[72:73], v[74:75], v[76:77]
	v_pk_add_f32 v[68:69], v[68:69], v[70:71]
	s_nop 0
	v_pk_add_f32 v[68:69], v[68:69], v[72:73]
	s_nop 0
	v_add_f32_e32 v60, v68, v69
	v_fmamk_f32 v60, v60, 0x3a800000, v152
	v_mul_f32_e32 v64, 0x4f800000, v60
	v_cmp_gt_f32_e32 vcc, s49, v60
	s_nop 1
	v_cndmask_b32_e32 v67, v60, v64, vcc
	v_sqrt_f32_e32 v68, v67
	v_mov_b32_e32 v64, v50
	v_mov_b32_e32 v60, v65
	v_mov_b32_e32 v65, v54
	v_add_u32_e32 v50, -1, v68
	v_add_u32_e32 v54, 1, v68
	v_fma_f32 v69, -v50, v68, v67
	v_fma_f32 v70, -v54, v68, v67
	v_cmp_ge_f32_e64 s[6:7], 0, v69
	s_nop 1
	v_cndmask_b32_e64 v50, v68, v50, s[6:7]
	v_cmp_lt_f32_e64 s[6:7], 0, v70
	s_nop 1
	v_cndmask_b32_e64 v50, v50, v54, s[6:7]
	v_mul_f32_e32 v54, 0x37800000, v50
	v_cndmask_b32_e32 v50, v50, v54, vcc
	v_cmp_class_f32_e32 vcc, v67, v153
	v_mov_b32_e32 v54, v51
	s_nop 0
	v_cndmask_b32_e32 v50, v50, v67, vcc
	v_div_scale_f32 v67, s[6:7], v50, v50, 1.0
	v_rcp_f32_e32 v68, v67
	v_div_scale_f32 v51, vcc, 1.0, v50, 1.0
	v_fma_f32 v69, -v67, v68, 1.0
	v_fmac_f32_e32 v68, v69, v68
	v_mul_f32_e32 v69, v51, v68
	v_fma_f32 v70, -v67, v69, v51
	v_fmac_f32_e32 v69, v70, v68
	v_fma_f32 v51, -v67, v69, v51
	v_div_fmas_f32 v51, v51, v68, v69
	v_div_fixup_f32 v50, v51, v50, 1.0
	v_pk_mul_f32 v[68:69], v[84:85], v[50:51] op_sel_hi:[1,0]
	v_pk_mul_f32 v[58:59], v[58:59], v[50:51] op_sel_hi:[1,0]
	v_pk_mul_f32 v[62:63], v[62:63], v[50:51] op_sel_hi:[1,0]
	v_pk_mul_f32 v[60:61], v[60:61], v[50:51] op_sel_hi:[1,0]
	v_pk_mul_f32 v[64:65], v[64:65], v[50:51] op_sel_hi:[1,0]
	v_pk_mul_f32 v[54:55], v[54:55], v[50:51] op_sel_hi:[1,0]
	v_mul_f32_e32 v51, 0xbfb8aa3b, v69
	v_mul_f32_e32 v67, 0xbfb8aa3b, v59
	v_mul_f32_e32 v71, 0xbfb8aa3b, v61
	v_mul_f32_e32 v72, 0xbfb8aa3b, v65
	v_exp_f32_e32 v51, v51
	v_exp_f32_e32 v67, v67
	v_exp_f32_e32 v71, v71
	v_exp_f32_e32 v72, v72
	v_mul_f32_e32 v70, 0xbfb8aa3b, v63
	v_exp_f32_e32 v70, v70
	v_add_f32_e32 v51, 1.0, v51
	v_add_f32_e32 v67, 1.0, v67
	v_add_f32_e32 v71, 1.0, v71
	v_add_f32_e32 v72, 1.0, v72
	v_rcp_f32_e32 v51, v51
	v_mul_f32_e32 v73, 0xbfb8aa3b, v55
	v_rcp_f32_e32 v67, v67
	v_rcp_f32_e32 v71, v71
	v_rcp_f32_e32 v72, v72
	v_exp_f32_e32 v73, v73
	v_add_f32_e32 v70, 1.0, v70
	v_rcp_f32_e32 v70, v70
	v_mul_f32_e32 v51, v69, v51
	v_mul_f32_e32 v59, v59, v67
	v_mul_f32_e32 v61, v61, v71
	v_mul_f32_e32 v67, v68, v51
	v_mul_f32_e32 v51, v65, v72
	v_mul_f32_e32 v68, v58, v59
	v_mul_f32_e32 v60, v60, v61
	v_mul_f32_e32 v61, v64, v51
	v_add_f32_e32 v51, 1.0, v73
	v_mov_b32_e32 v58, v52
	v_mov_b32_e32 v59, v56
	v_mul_f32_e32 v63, v63, v70
	v_pk_mul_f32 v[58:59], v[58:59], v[50:51] op_sel_hi:[1,0]
	v_mul_f32_e32 v62, v62, v63
	v_rcp_f32_e32 v63, v51
	v_mul_f32_e32 v51, 0xbfb8aa3b, v59
	v_mov_b32_e32 v56, v53
	v_exp_f32_e32 v52, v51
	v_pk_mul_f32 v[50:51], v[56:57], v[50:51] op_sel_hi:[1,0]
	v_mul_f32_e32 v55, v55, v63
	v_mul_f32_e32 v53, 0xbfb8aa3b, v51
	v_exp_f32_e32 v53, v53
	v_add_f32_e32 v52, 1.0, v52
	v_rcp_f32_e32 v52, v52
	v_mul_f32_e32 v54, v54, v55
	v_add_f32_e32 v53, 1.0, v53
	v_rcp_f32_e32 v53, v53
	v_mul_f32_e32 v52, v59, v52
	v_mul_f32_e32 v55, v58, v52
	v_mov_b32_e32 v69, v42
	v_mul_f32_e32 v51, v51, v53
	v_mul_f32_e32 v53, v50, v51
	v_cvt_pk_bf16_f32 v50, v67, v68
	v_cvt_pk_bf16_f32 v51, v62, v60
	v_cvt_pk_bf16_f32 v52, v61, v54
	v_cvt_pk_bf16_f32 v53, v55, v53
	v_mad_i64_i32 v[54:55], s[6:7], v66, s50, v[114:115]
	v_add_u32_e32 v66, 0x90, v146
	v_lshl_add_u64 v[54:55], v[54:55], 0, v[116:117]
	v_ashrrev_i32_e32 v67, 31, v66
	global_store_dwordx4 v[54:55], v[50:53], off nt
	v_mov_b32_e32 v42, v47
	v_mov_b32_e32 v68, v46
	v_lshlrev_b64 v[50:51], 6, v[66:67]
	v_lshl_add_u64 v[62:63], s[8:9], 0, v[50:51]
	s_waitcnt vmcnt(6)
	v_mov_b32_e32 v50, v192
	v_mov_b32_e32 v51, v193
	v_mov_b32_e32 v52, v194
	v_mov_b32_e32 v53, v195
	v_mov_b32_e32 v54, v196
	v_mov_b32_e32 v55, v197
	v_mov_b32_e32 v56, v198
	v_mov_b32_e32 v57, v199
	v_mov_b32_e32 v58, v200
	v_mov_b32_e32 v59, v201
	v_mov_b32_e32 v60, v202
	v_mov_b32_e32 v61, v203
	v_mov_b32_e32 v62, v204
	v_mov_b32_e32 v63, v205
	v_mov_b32_e32 v64, v206
	v_mov_b32_e32 v65, v207
	global_load_dwordx4 v[192:195], v[210:211], off offset:3072
	global_load_dwordx4 v[196:199], v[210:211], off offset:3088
	global_load_dwordx4 v[200:203], v[210:211], off offset:3104
	global_load_dwordx4 v[204:207], v[210:211], off offset:3120
	v_mov_b32_e32 v46, v48
	v_mov_b32_e32 v70, v51
	v_mov_b32_e32 v71, v52
	v_mov_b32_e32 v51, v53
	v_mov_b32_e32 v52, v55
	v_mov_b32_e32 v53, v56
	v_mov_b32_e32 v55, v57
	v_pk_add_f32 v[50:51], v[70:71], v[50:51]
	v_pk_add_f32 v[52:53], v[52:53], v[54:55]
	v_pk_add_f32 v[50:51], v[50:51], v[50:51] op_sel:[0,1] op_sel_hi:[1,0]
	v_pk_add_f32 v[52:53], v[52:53], v[52:53] op_sel:[0,1] op_sel_hi:[1,0]
	v_add_f32_e32 v56, v58, v59
	v_add_f32_e32 v58, v60, v61
	v_mov_b32_e32 v57, v64
	v_mov_b32_e32 v59, v65
	v_mov_b32_e32 v51, v62
	v_mov_b32_e32 v53, v63
	v_pk_add_f32 v[54:55], v[56:57], v[58:59]
	v_pk_add_f32 v[50:51], v[50:51], v[52:53]
	s_nop 0
	v_pk_add_f32 v[50:51], v[50:51], v[54:55]
	s_nop 0
	v_add_f32_e32 v47, v50, v51
	v_fmamk_f32 v47, v47, 0x3a800000, v152
	v_mul_f32_e32 v48, 0x4f800000, v47
	v_cmp_gt_f32_e32 vcc, s49, v47
	s_nop 1
	v_cndmask_b32_e32 v50, v47, v48, vcc
	v_sqrt_f32_e32 v51, v50
	v_mov_b32_e32 v48, v34
	v_mov_b32_e32 v47, v44
	v_mov_b32_e32 v44, v49
	v_add_u32_e32 v34, -1, v51
	v_add_u32_e32 v49, 1, v51
	v_fma_f32 v52, -v34, v51, v50
	v_fma_f32 v53, -v49, v51, v50
	v_cmp_ge_f32_e64 s[6:7], 0, v52
	s_nop 1
	v_cndmask_b32_e64 v34, v51, v34, s[6:7]
	v_cmp_lt_f32_e64 s[6:7], 0, v53
	s_nop 1
	v_cndmask_b32_e64 v34, v34, v49, s[6:7]
	v_mul_f32_e32 v49, 0x37800000, v34
	v_cndmask_b32_e32 v34, v34, v49, vcc
	v_cmp_class_f32_e32 vcc, v50, v153
	v_mov_b32_e32 v49, v38
	s_nop 0
	v_cndmask_b32_e32 v34, v34, v50, vcc
	v_div_scale_f32 v50, s[6:7], v34, v34, 1.0
	v_rcp_f32_e32 v51, v50
	v_div_scale_f32 v38, vcc, 1.0, v34, 1.0
	v_fma_f32 v52, -v50, v51, 1.0
	v_fmac_f32_e32 v51, v52, v51
	v_mul_f32_e32 v52, v38, v51
	v_fma_f32 v53, -v50, v52, v38
	v_fmac_f32_e32 v52, v53, v51
	v_fma_f32 v38, -v50, v52, v38
	v_div_fmas_f32 v38, v38, v51, v52
	v_div_fixup_f32 v34, v38, v34, 1.0
	v_pk_mul_f32 v[50:51], v[68:69], v[34:35] op_sel_hi:[1,0]
	v_pk_mul_f32 v[42:43], v[42:43], v[34:35] op_sel_hi:[1,0]
	v_mul_f32_e32 v38, 0xbfb8aa3b, v51
	v_mul_f32_e32 v52, 0xbfb8aa3b, v43
	v_exp_f32_e32 v38, v38
	v_exp_f32_e32 v52, v52
	v_pk_mul_f32 v[48:49], v[48:49], v[34:35] op_sel_hi:[1,0]
	v_pk_mul_f32 v[44:45], v[44:45], v[34:35] op_sel_hi:[1,0]
	v_add_f32_e32 v38, 1.0, v38
	v_mul_f32_e32 v55, 0xbfb8aa3b, v49
	v_add_f32_e32 v52, 1.0, v52
	v_rcp_f32_e32 v38, v38
	v_exp_f32_e32 v55, v55
	v_rcp_f32_e32 v52, v52
	v_mul_f32_e32 v54, 0xbfb8aa3b, v45
	v_pk_mul_f32 v[46:47], v[46:47], v[34:35] op_sel_hi:[1,0]
	v_exp_f32_e32 v54, v54
	v_mul_f32_e32 v53, 0xbfb8aa3b, v47
	v_mul_f32_e32 v38, v51, v38
	v_exp_f32_e32 v53, v53
	v_mul_f32_e32 v43, v43, v52
	v_mul_f32_e32 v50, v50, v38
	v_add_f32_e32 v38, 1.0, v55
	v_mul_f32_e32 v51, v42, v43
	v_rcp_f32_e32 v42, v38
	v_mov_b32_e32 v38, v35
	v_add_f32_e32 v54, 1.0, v54
	v_pk_mul_f32 v[38:39], v[38:39], v[34:35] op_sel_hi:[1,0]
	v_rcp_f32_e32 v54, v54
	v_mul_f32_e32 v35, 0xbfb8aa3b, v39
	v_add_f32_e32 v53, 1.0, v53
	v_exp_f32_e32 v35, v35
	v_rcp_f32_e32 v53, v53
	v_mul_f32_e32 v45, v45, v54
	v_mul_f32_e32 v42, v49, v42
	v_mul_f32_e32 v44, v44, v45
	v_mul_f32_e32 v45, v48, v42
	v_add_f32_e32 v35, 1.0, v35
	v_mov_b32_e32 v42, v36
	v_mov_b32_e32 v43, v40
	v_mul_f32_e32 v47, v47, v53
	v_pk_mul_f32 v[42:43], v[42:43], v[34:35] op_sel_hi:[1,0]
	v_mul_f32_e32 v46, v46, v47
	v_rcp_f32_e32 v47, v35
	v_mul_f32_e32 v35, 0xbfb8aa3b, v43
	v_mov_b32_e32 v40, v37
	v_exp_f32_e32 v36, v35
	v_pk_mul_f32 v[34:35], v[40:41], v[34:35] op_sel_hi:[1,0]
	v_mul_f32_e32 v39, v39, v47
	v_mul_f32_e32 v37, 0xbfb8aa3b, v35
	v_exp_f32_e32 v37, v37
	v_add_f32_e32 v36, 1.0, v36
	v_rcp_f32_e32 v36, v36
	v_mul_f32_e32 v38, v38, v39
	v_add_f32_e32 v37, 1.0, v37
	v_rcp_f32_e32 v37, v37
	v_mul_f32_e32 v36, v43, v36
	v_mul_f32_e32 v39, v42, v36
	v_mov_b32_e32 v53, v26
	v_mul_f32_e32 v35, v35, v37
	v_mul_f32_e32 v37, v34, v35
	v_cvt_pk_bf16_f32 v34, v50, v51
	v_cvt_pk_bf16_f32 v35, v46, v44
	v_cvt_pk_bf16_f32 v36, v45, v38
	v_cvt_pk_bf16_f32 v37, v39, v37
	v_mad_i64_i32 v[38:39], s[6:7], v66, s50, v[114:115]
	v_add_u32_e32 v50, 0xa0, v146
	v_lshl_add_u64 v[38:39], v[38:39], 0, v[116:117]
	v_ashrrev_i32_e32 v51, 31, v50
	global_store_dwordx4 v[38:39], v[34:37], off nt
	v_mov_b32_e32 v26, v31
	v_mov_b32_e32 v52, v30
	v_lshlrev_b64 v[34:35], 6, v[50:51]
	v_lshl_add_u64 v[46:47], s[8:9], 0, v[34:35]
	s_waitcnt vmcnt(6)
	v_mov_b32_e32 v34, v176
	v_mov_b32_e32 v35, v177
	v_mov_b32_e32 v36, v178
	v_mov_b32_e32 v37, v179
	v_mov_b32_e32 v38, v180
	v_mov_b32_e32 v39, v181
	v_mov_b32_e32 v40, v182
	v_mov_b32_e32 v41, v183
	v_mov_b32_e32 v42, v184
	v_mov_b32_e32 v43, v185
	v_mov_b32_e32 v44, v186
	v_mov_b32_e32 v45, v187
	v_mov_b32_e32 v46, v188
	v_mov_b32_e32 v47, v189
	v_mov_b32_e32 v48, v190
	v_mov_b32_e32 v49, v191
	v_mov_b32_e32 v30, v32
	v_mov_b32_e32 v54, v35
	v_mov_b32_e32 v55, v36
	v_mov_b32_e32 v35, v37
	v_mov_b32_e32 v36, v39
	v_mov_b32_e32 v37, v40
	v_mov_b32_e32 v39, v41
	v_pk_add_f32 v[34:35], v[54:55], v[34:35]
	v_pk_add_f32 v[36:37], v[36:37], v[38:39]
	v_pk_add_f32 v[34:35], v[34:35], v[34:35] op_sel:[0,1] op_sel_hi:[1,0]
	v_pk_add_f32 v[36:37], v[36:37], v[36:37] op_sel:[0,1] op_sel_hi:[1,0]
	v_add_f32_e32 v40, v42, v43
	v_add_f32_e32 v42, v44, v45
	v_mov_b32_e32 v41, v48
	v_mov_b32_e32 v43, v49
	v_mov_b32_e32 v35, v46
	v_mov_b32_e32 v37, v47
	v_pk_add_f32 v[38:39], v[40:41], v[42:43]
	v_pk_add_f32 v[34:35], v[34:35], v[36:37]
	s_nop 0
	v_pk_add_f32 v[34:35], v[34:35], v[38:39]
	s_nop 0
	v_add_f32_e32 v31, v34, v35
	v_fmamk_f32 v31, v31, 0x3a800000, v152
	v_mul_f32_e32 v32, 0x4f800000, v31
	v_cmp_gt_f32_e32 vcc, s49, v31
	s_nop 1
	v_cndmask_b32_e32 v34, v31, v32, vcc
	v_sqrt_f32_e32 v35, v34
	v_mov_b32_e32 v32, v18
	v_mov_b32_e32 v31, v28
	v_mov_b32_e32 v28, v33
	v_add_u32_e32 v18, -1, v35
	v_add_u32_e32 v33, 1, v35
	v_fma_f32 v36, -v18, v35, v34
	v_fma_f32 v37, -v33, v35, v34
	v_cmp_ge_f32_e64 s[6:7], 0, v36
	s_nop 1
	v_cndmask_b32_e64 v18, v35, v18, s[6:7]
	v_cmp_lt_f32_e64 s[6:7], 0, v37
	s_nop 1
	v_cndmask_b32_e64 v18, v18, v33, s[6:7]
	v_mul_f32_e32 v33, 0x37800000, v18
	v_cndmask_b32_e32 v18, v18, v33, vcc
	v_cmp_class_f32_e32 vcc, v34, v153
	v_mov_b32_e32 v33, v22
	s_nop 0
	v_cndmask_b32_e32 v18, v18, v34, vcc
	v_div_scale_f32 v34, s[6:7], v18, v18, 1.0
	v_rcp_f32_e32 v35, v34
	v_div_scale_f32 v22, vcc, 1.0, v18, 1.0
	v_fma_f32 v36, -v34, v35, 1.0
	v_fmac_f32_e32 v35, v36, v35
	v_mul_f32_e32 v36, v22, v35
	v_fma_f32 v37, -v34, v36, v22
	v_fmac_f32_e32 v36, v37, v35
	v_fma_f32 v22, -v34, v36, v22
	v_div_fmas_f32 v22, v22, v35, v36
	v_div_fixup_f32 v18, v22, v18, 1.0
	v_pk_mul_f32 v[26:27], v[26:27], v[18:19] op_sel_hi:[1,0]
	v_pk_mul_f32 v[34:35], v[52:53], v[18:19] op_sel_hi:[1,0]
	v_mul_f32_e32 v36, 0xbfb8aa3b, v27
	v_mul_f32_e32 v22, 0xbfb8aa3b, v35
	v_exp_f32_e32 v36, v36
	v_exp_f32_e32 v22, v22
	v_pk_mul_f32 v[30:31], v[30:31], v[18:19] op_sel_hi:[1,0]
	v_pk_mul_f32 v[28:29], v[28:29], v[18:19] op_sel_hi:[1,0]
	v_add_f32_e32 v36, 1.0, v36
	v_add_f32_e32 v22, 1.0, v22
	v_rcp_f32_e32 v36, v36
	v_mul_f32_e32 v37, 0xbfb8aa3b, v31
	v_rcp_f32_e32 v22, v22
	v_exp_f32_e32 v37, v37
	v_mul_f32_e32 v27, v27, v36
	v_mul_f32_e32 v38, 0xbfb8aa3b, v29
	v_mul_f32_e32 v22, v35, v22
	v_mul_f32_e32 v35, v26, v27
	v_pk_mul_f32 v[26:27], v[32:33], v[18:19] op_sel_hi:[1,0]
	v_add_f32_e32 v37, 1.0, v37
	v_mul_f32_e32 v34, v34, v22
	v_mul_f32_e32 v22, 0xbfb8aa3b, v27
	v_rcp_f32_e32 v37, v37
	v_exp_f32_e32 v22, v22
	v_exp_f32_e32 v38, v38
	v_mov_b32_e32 v36, v10
	v_mul_f32_e32 v31, v31, v37
	v_add_f32_e32 v22, 1.0, v22
	v_mul_f32_e32 v30, v30, v31
	v_rcp_f32_e32 v31, v22
	v_mov_b32_e32 v22, v19
	v_add_f32_e32 v38, 1.0, v38
	v_pk_mul_f32 v[22:23], v[22:23], v[18:19] op_sel_hi:[1,0]
	v_rcp_f32_e32 v38, v38
	v_mul_f32_e32 v19, 0xbfb8aa3b, v23
	v_exp_f32_e32 v19, v19
	v_mul_f32_e32 v27, v27, v31
	v_mul_f32_e32 v29, v29, v38
	v_mul_f32_e32 v28, v28, v29
	v_mul_f32_e32 v29, v26, v27
	v_add_f32_e32 v19, 1.0, v19
	v_mov_b32_e32 v26, v20
	v_mov_b32_e32 v27, v24
	v_pk_mul_f32 v[26:27], v[26:27], v[18:19] op_sel_hi:[1,0]
	v_rcp_f32_e32 v31, v19
	v_mul_f32_e32 v19, 0xbfb8aa3b, v27
	v_mov_b32_e32 v24, v21
	v_exp_f32_e32 v20, v19
	v_pk_mul_f32 v[18:19], v[24:25], v[18:19] op_sel_hi:[1,0]
	v_mul_f32_e32 v23, v23, v31
	v_mul_f32_e32 v21, 0xbfb8aa3b, v19
	v_exp_f32_e32 v21, v21
	v_add_f32_e32 v20, 1.0, v20
	v_rcp_f32_e32 v20, v20
	v_mul_f32_e32 v22, v22, v23
	v_add_f32_e32 v21, 1.0, v21
	v_rcp_f32_e32 v21, v21
	v_mul_f32_e32 v20, v27, v20
	v_mul_f32_e32 v23, v26, v20
	v_mov_b32_e32 v37, v14
	v_mul_f32_e32 v19, v19, v21
	v_mul_f32_e32 v21, v18, v19
	v_cvt_pk_bf16_f32 v18, v34, v35
	v_cvt_pk_bf16_f32 v19, v30, v28
	v_cvt_pk_bf16_f32 v20, v29, v22
	v_cvt_pk_bf16_f32 v21, v23, v21
	v_mad_i64_i32 v[22:23], s[6:7], v50, s50, v[114:115]
	v_add_u32_e32 v34, 0xb0, v146
	v_lshl_add_u64 v[22:23], v[22:23], 0, v[116:117]
	v_ashrrev_i32_e32 v35, 31, v34
	global_store_dwordx4 v[22:23], v[18:21], off nt
	s_nop 1
	v_lshlrev_b64 v[18:19], 6, v[34:35]
	v_lshl_add_u64 v[30:31], s[8:9], 0, v[18:19]
	s_waitcnt vmcnt(2)
	v_mov_b32_e32 v18, v192
	v_mov_b32_e32 v19, v193
	v_mov_b32_e32 v20, v194
	v_mov_b32_e32 v21, v195
	v_mov_b32_e32 v22, v196
	v_mov_b32_e32 v23, v197
	v_mov_b32_e32 v24, v198
	v_mov_b32_e32 v25, v199
	v_mov_b32_e32 v26, v200
	v_mov_b32_e32 v27, v201
	v_mov_b32_e32 v28, v202
	v_mov_b32_e32 v29, v203
	v_mov_b32_e32 v30, v204
	v_mov_b32_e32 v31, v205
	v_mov_b32_e32 v32, v206
	v_mov_b32_e32 v33, v207
	v_mov_b32_e32 v38, v19
	v_mov_b32_e32 v39, v20
	v_mov_b32_e32 v19, v21
	v_mov_b32_e32 v20, v23
	v_mov_b32_e32 v21, v24
	v_mov_b32_e32 v23, v25
	v_pk_add_f32 v[18:19], v[38:39], v[18:19]
	v_pk_add_f32 v[20:21], v[20:21], v[22:23]
	v_pk_add_f32 v[18:19], v[18:19], v[18:19] op_sel:[0,1] op_sel_hi:[1,0]
	v_pk_add_f32 v[20:21], v[20:21], v[20:21] op_sel:[0,1] op_sel_hi:[1,0]
	v_add_f32_e32 v24, v26, v27
	v_add_f32_e32 v26, v28, v29
	v_mov_b32_e32 v25, v32
	v_mov_b32_e32 v27, v33
	v_mov_b32_e32 v19, v30
	v_mov_b32_e32 v21, v31
	v_pk_add_f32 v[22:23], v[24:25], v[26:27]
	v_pk_add_f32 v[18:19], v[18:19], v[20:21]
	s_nop 0
	v_pk_add_f32 v[18:19], v[18:19], v[22:23]
	s_nop 0
	v_add_f32_e32 v10, v18, v19
	v_fmamk_f32 v10, v10, 0x3a800000, v152
	v_mul_f32_e32 v14, 0x4f800000, v10
	v_cmp_gt_f32_e32 vcc, s49, v10
	s_nop 1
	v_cndmask_b32_e32 v18, v10, v14, vcc
	v_sqrt_f32_e32 v19, v18
	v_mov_b32_e32 v10, v12
	v_mov_b32_e32 v14, v11
	v_mov_b32_e32 v11, v16
	v_add_u32_e32 v12, -1, v19
	v_add_u32_e32 v16, 1, v19
	v_fma_f32 v20, -v12, v19, v18
	v_fma_f32 v21, -v16, v19, v18
	v_cmp_ge_f32_e64 s[6:7], 0, v20
	s_nop 1
	v_cndmask_b32_e64 v12, v19, v12, s[6:7]
	v_cmp_lt_f32_e64 s[6:7], 0, v21
	s_nop 1
	v_cndmask_b32_e64 v12, v12, v16, s[6:7]
	v_mul_f32_e32 v16, 0x37800000, v12
	v_cndmask_b32_e32 v12, v12, v16, vcc
	v_cmp_class_f32_e32 vcc, v18, v153
	v_mov_b32_e32 v16, v13
	s_nop 0
	v_cndmask_b32_e32 v12, v12, v18, vcc
	v_div_scale_f32 v18, s[6:7], v12, v12, 1.0
	v_rcp_f32_e32 v19, v18
	v_div_scale_f32 v13, vcc, 1.0, v12, 1.0
	v_fma_f32 v20, -v18, v19, 1.0
	v_fmac_f32_e32 v19, v20, v19
	v_mul_f32_e32 v20, v13, v19
	v_fma_f32 v21, -v18, v20, v13
	v_fmac_f32_e32 v20, v21, v19
	v_fma_f32 v13, -v18, v20, v13
	v_div_fmas_f32 v13, v13, v19, v20
	v_div_fixup_f32 v12, v13, v12, 1.0
	v_pk_mul_f32 v[18:19], v[36:37], v[12:13] op_sel_hi:[1,0]
	v_pk_mul_f32 v[14:15], v[14:15], v[12:13] op_sel_hi:[1,0]
	v_pk_mul_f32 v[10:11], v[10:11], v[12:13] op_sel_hi:[1,0]
	v_pk_mul_f32 v[16:17], v[16:17], v[12:13] op_sel_hi:[1,0]
	v_mul_f32_e32 v13, 0xbfb8aa3b, v19
	v_mul_f32_e32 v20, 0xbfb8aa3b, v15
	v_exp_f32_e32 v13, v13
	v_exp_f32_e32 v20, v20
	v_mul_f32_e32 v21, 0xbfb8aa3b, v11
	v_mul_f32_e32 v22, 0xbfb8aa3b, v17
	v_add_f32_e32 v13, 1.0, v13
	v_add_f32_e32 v20, 1.0, v20
	v_rcp_f32_e32 v13, v13
	v_rcp_f32_e32 v20, v20
	v_exp_f32_e32 v21, v21
	v_exp_f32_e32 v22, v22
	v_mul_f32_e32 v13, v19, v13
	v_mul_f32_e32 v15, v15, v20
	v_mul_f32_e32 v13, v18, v13
	v_mul_f32_e32 v18, v14, v15
	v_add_f32_e32 v14, 1.0, v21
	v_rcp_f32_e32 v19, v14
	v_add_f32_e32 v14, 1.0, v22
	v_rcp_f32_e32 v20, v14
	v_mov_b32_e32 v14, v2
	v_mov_b32_e32 v15, v6
	v_pk_mul_f32 v[14:15], v[14:15], v[12:13] op_sel_hi:[1,0]
	v_mul_f32_e32 v6, v11, v19
	v_mul_f32_e32 v2, 0xbfb8aa3b, v15
	v_exp_f32_e32 v2, v2
	v_mul_f32_e32 v10, v10, v6
	v_mov_b32_e32 v6, v3
	v_mul_f32_e32 v11, v17, v20
	v_add_f32_e32 v2, 1.0, v2
	v_rcp_f32_e32 v17, v2
	v_pk_mul_f32 v[2:3], v[6:7], v[12:13] op_sel_hi:[1,0]
	v_mul_f32_e32 v11, v16, v11
	v_mul_f32_e32 v6, 0xbfb8aa3b, v3
	v_exp_f32_e32 v6, v6
	v_mul_f32_e32 v7, v15, v17
	v_mul_f32_e32 v14, v14, v7
	v_mov_b32_e32 v7, v8
	v_add_f32_e32 v6, 1.0, v6
	v_rcp_f32_e32 v15, v6
	v_mov_b32_e32 v6, v4
	v_pk_mul_f32 v[6:7], v[6:7], v[12:13] op_sel_hi:[1,0]
	v_mov_b32_e32 v8, v5
	v_mul_f32_e32 v4, 0xbfb8aa3b, v7
	v_exp_f32_e32 v16, v4
	v_pk_mul_f32 v[4:5], v[8:9], v[12:13] op_sel_hi:[1,0]
	v_mul_f32_e32 v3, v3, v15
	v_mul_f32_e32 v8, 0xbfb8aa3b, v5
	v_exp_f32_e32 v8, v8
	v_add_f32_e32 v9, 1.0, v16
	v_rcp_f32_e32 v9, v9
	v_mul_f32_e32 v12, v2, v3
	v_add_f32_e32 v8, 1.0, v8
	v_rcp_f32_e32 v8, v8
	v_mul_f32_e32 v2, v7, v9
	v_mul_f32_e32 v6, v6, v2
	s_andn2_b64 vcc, exec, s[4:5]
	v_mul_f32_e32 v2, v5, v8
	v_mul_f32_e32 v5, v4, v2
	v_cvt_pk_bf16_f32 v2, v13, v18
	v_cvt_pk_bf16_f32 v3, v10, v11
	v_cvt_pk_bf16_f32 v4, v14, v12
	v_cvt_pk_bf16_f32 v5, v6, v5
	v_mad_i64_i32 v[6:7], s[6:7], v34, s50, v[114:115]
	v_lshl_add_u64 v[6:7], v[6:7], 0, v[116:117]
	s_mov_b64 s[4:5], -1
	global_store_dwordx4 v[6:7], v[2:5], off nt
	s_cbranch_vccnz .LBB0_248
	s_andn2_b64 vcc, exec, s[2:3]
	s_cbranch_vccnz .LBB0_247
	s_barrier
	s_branch .LBB0_247

.LBB0_2429:
	ds_read_b128 v[156:159], v149
	ds_read_b128 v[160:163], v149 offset:1024
	ds_read_b128 v[164:167], v149 offset:2048
	ds_read_b128 v[168:171], v149 offset:3072
	ds_read_b128 v[172:175], v150
	ds_read_b128 v[176:179], v150 offset:1024
	ds_read_b128 v[180:183], v150 offset:2048
	ds_read_b128 v[184:187], v150 offset:3072
	s_add_u32 s26, s24, 0xfffc0080
	s_addc_u32 s27, s25, -1
	s_cmp_eq_u32 s57, 12
	s_cselect_b32 s29, s19, s27
	s_cselect_b32 s28, s53, s26
	s_cselect_b32 s27, s17, s56
	s_cselect_b32 s26, s54, s55
	v_lshl_add_u64 v[146:147], s[24:25], 0, v[138:139]
	s_add_i32 m0, s38, 0xc000
	ds_read_b128 v[188:191], v151
	ds_read_b128 v[192:195], v151 offset:1024
	ds_read_b128 v[196:199], v151 offset:2048
	ds_read_b128 v[200:203], v151 offset:3072
	ds_read_b128 v[204:207], v151 offset:4096
	ds_read_b128 v[208:211], v151 offset:5120
	ds_read_b128 v[212:215], v151 offset:6144
	ds_read_b128 v[216:219], v151 offset:7168
	global_load_lds_dwordx4 v[146:147], off
	v_lshl_add_u64 v[146:147], s[24:25], 0, v[140:141]
	s_add_i32 m0, s38, 0xe000
	s_nop 0
	global_load_lds_dwordx4 v[146:147], off
	s_waitcnt vmcnt(8)
	s_waitcnt lgkmcnt(0)
	s_barrier
	s_setprio 1
	s_waitcnt lgkmcnt(0)
	v_mfma_f32_16x16x32_bf16 v[122:125], v[156:159], v[188:191], v[122:125]
	v_mfma_f32_16x16x32_bf16 v[114:117], v[164:167], v[188:191], v[114:117]
	v_mfma_f32_16x16x32_bf16 v[106:109], v[156:159], v[196:199], v[106:109]
	v_mfma_f32_16x16x32_bf16 v[102:105], v[164:167], v[196:199], v[102:105]
	v_mfma_f32_16x16x32_bf16 v[90:93], v[156:159], v[204:207], v[90:93]
	v_mfma_f32_16x16x32_bf16 v[86:89], v[164:167], v[204:207], v[86:89]
	v_mfma_f32_16x16x32_bf16 v[74:77], v[156:159], v[212:215], v[74:77]
	v_mfma_f32_16x16x32_bf16 v[70:73], v[164:167], v[212:215], v[70:73]
	v_mfma_f32_16x16x32_bf16 v[122:125], v[160:163], v[192:195], v[122:125]
	v_mfma_f32_16x16x32_bf16 v[114:117], v[168:171], v[192:195], v[114:117]
	v_mfma_f32_16x16x32_bf16 v[106:109], v[160:163], v[200:203], v[106:109]
	v_mfma_f32_16x16x32_bf16 v[102:105], v[168:171], v[200:203], v[102:105]
	v_mfma_f32_16x16x32_bf16 v[90:93], v[160:163], v[208:211], v[90:93]
	v_mfma_f32_16x16x32_bf16 v[86:89], v[168:171], v[208:211], v[86:89]
	v_mfma_f32_16x16x32_bf16 v[74:77], v[160:163], v[216:219], v[74:77]
	v_mfma_f32_16x16x32_bf16 v[70:73], v[168:171], v[216:219], v[70:73]
	s_setprio 0
	s_setprio 1
	v_mfma_f32_16x16x32_bf16 v[126:129], v[172:175], v[188:191], v[126:129]
	v_mfma_f32_16x16x32_bf16 v[118:121], v[180:183], v[188:191], v[118:121]
	v_mfma_f32_16x16x32_bf16 v[110:113], v[172:175], v[196:199], v[110:113]
	v_mfma_f32_16x16x32_bf16 v[98:101], v[180:183], v[196:199], v[98:101]
	v_mfma_f32_16x16x32_bf16 v[94:97], v[172:175], v[204:207], v[94:97]
	v_mfma_f32_16x16x32_bf16 v[82:85], v[180:183], v[204:207], v[82:85]
	v_mfma_f32_16x16x32_bf16 v[78:81], v[172:175], v[212:215], v[78:81]
	v_mfma_f32_16x16x32_bf16 v[66:69], v[180:183], v[212:215], v[66:69]
	v_mfma_f32_16x16x32_bf16 v[126:129], v[176:179], v[192:195], v[126:129]
	v_mfma_f32_16x16x32_bf16 v[118:121], v[184:187], v[192:195], v[118:121]
	v_mfma_f32_16x16x32_bf16 v[110:113], v[176:179], v[200:203], v[110:113]
	v_mfma_f32_16x16x32_bf16 v[98:101], v[184:187], v[200:203], v[98:101]
	v_mfma_f32_16x16x32_bf16 v[94:97], v[176:179], v[208:211], v[94:97]
	v_mfma_f32_16x16x32_bf16 v[82:85], v[184:187], v[208:211], v[82:85]
	v_mfma_f32_16x16x32_bf16 v[78:81], v[176:179], v[216:219], v[78:81]
	v_mfma_f32_16x16x32_bf16 v[66:69], v[184:187], v[216:219], v[66:69]
	s_setprio 0
	s_barrier
	s_add_i32 s58, s47, s35
	v_lshl_add_u64 v[146:147], s[26:27], 0, v[134:135]
	s_mov_b32 m0, s58
	ds_read_b128 v[188:191], v151 offset:16384
	ds_read_b128 v[192:195], v151 offset:17408
	ds_read_b128 v[196:199], v151 offset:18432
	ds_read_b128 v[200:203], v151 offset:19456
	ds_read_b128 v[204:207], v151 offset:20480
	ds_read_b128 v[208:211], v151 offset:21504
	ds_read_b128 v[212:215], v151 offset:22528
	ds_read_b128 v[216:219], v151 offset:23552
	global_load_lds_dwordx4 v[146:147], off
	s_add_i32 m0, s58, 0x2000
	s_add_u32 s58, s26, 0x40000
	v_lshl_add_u64 v[220:221], s[26:27], 0, v[130:131]
	s_addc_u32 s59, s27, 0
	s_add_i32 s60, s48, s35
	global_load_lds_dwordx4 v[220:221], off
	v_lshl_add_u64 v[222:223], s[58:59], 0, v[134:135]
	s_mov_b32 m0, s60
	v_lshl_add_u64 v[224:225], s[28:29], 0, v[132:133]
	global_load_lds_dwordx4 v[222:223], off
	v_lshl_add_u64 v[222:223], s[58:59], 0, v[130:131]
	s_add_i32 m0, s60, 0x2000
	s_nop 0
	global_load_lds_dwordx4 v[222:223], off
	v_lshl_add_u64 v[222:223], s[28:29], 0, v[136:137]
	s_mov_b32 m0, s38
	s_nop 0
	global_load_lds_dwordx4 v[222:223], off
	s_mov_b32 m0, s39
	s_nop 0
	global_load_lds_dwordx4 v[224:225], off
	s_waitcnt vmcnt(8)
	s_waitcnt lgkmcnt(0)
	s_barrier
	s_setprio 1
	s_waitcnt lgkmcnt(0)
	v_mfma_f32_16x16x32_bf16 v[58:61], v[156:159], v[188:191], v[58:61]
	v_mfma_f32_16x16x32_bf16 v[54:57], v[164:167], v[188:191], v[54:57]
	v_mfma_f32_16x16x32_bf16 v[42:45], v[156:159], v[196:199], v[42:45]
	v_mfma_f32_16x16x32_bf16 v[38:41], v[164:167], v[196:199], v[38:41]
	v_mfma_f32_16x16x32_bf16 v[26:29], v[156:159], v[204:207], v[26:29]
	v_mfma_f32_16x16x32_bf16 v[22:25], v[164:167], v[204:207], v[22:25]
	v_mfma_f32_16x16x32_bf16 v[14:17], v[156:159], v[212:215], v[14:17]
	v_mfma_f32_16x16x32_bf16 v[6:9], v[164:167], v[212:215], v[6:9]
	v_mfma_f32_16x16x32_bf16 v[58:61], v[160:163], v[192:195], v[58:61]
	v_mfma_f32_16x16x32_bf16 v[54:57], v[168:171], v[192:195], v[54:57]
	v_mfma_f32_16x16x32_bf16 v[42:45], v[160:163], v[200:203], v[42:45]
	v_mfma_f32_16x16x32_bf16 v[38:41], v[168:171], v[200:203], v[38:41]
	v_mfma_f32_16x16x32_bf16 v[26:29], v[160:163], v[208:211], v[26:29]
	v_mfma_f32_16x16x32_bf16 v[22:25], v[168:171], v[208:211], v[22:25]
	v_mfma_f32_16x16x32_bf16 v[14:17], v[160:163], v[216:219], v[14:17]
	v_mfma_f32_16x16x32_bf16 v[6:9], v[168:171], v[216:219], v[6:9]
	s_setprio 0
	s_setprio 1
	v_mfma_f32_16x16x32_bf16 v[62:65], v[172:175], v[188:191], v[62:65]
	v_mfma_f32_16x16x32_bf16 v[50:53], v[180:183], v[188:191], v[50:53]
	v_mfma_f32_16x16x32_bf16 v[46:49], v[172:175], v[196:199], v[46:49]
	v_mfma_f32_16x16x32_bf16 v[34:37], v[180:183], v[196:199], v[34:37]
	v_mfma_f32_16x16x32_bf16 v[30:33], v[172:175], v[204:207], v[30:33]
	v_mfma_f32_16x16x32_bf16 v[18:21], v[180:183], v[204:207], v[18:21]
	v_mfma_f32_16x16x32_bf16 v[10:13], v[172:175], v[212:215], v[10:13]
	v_mfma_f32_16x16x32_bf16 v[2:5], v[180:183], v[212:215], v[2:5]
	v_mfma_f32_16x16x32_bf16 v[62:65], v[176:179], v[192:195], v[62:65]
	v_mfma_f32_16x16x32_bf16 v[50:53], v[184:187], v[192:195], v[50:53]
	v_mfma_f32_16x16x32_bf16 v[46:49], v[176:179], v[200:203], v[46:49]
	v_mfma_f32_16x16x32_bf16 v[34:37], v[184:187], v[200:203], v[34:37]
	v_mfma_f32_16x16x32_bf16 v[30:33], v[176:179], v[208:211], v[30:33]
	v_mfma_f32_16x16x32_bf16 v[18:21], v[184:187], v[208:211], v[18:21]
	v_mfma_f32_16x16x32_bf16 v[10:13], v[176:179], v[216:219], v[10:13]
	v_mfma_f32_16x16x32_bf16 v[2:5], v[184:187], v[216:219], v[2:5]
	s_setprio 0
	s_barrier
	ds_read_b128 v[156:159], v154
	ds_read_b128 v[160:163], v154 offset:1024
	ds_read_b128 v[164:167], v154 offset:2048
	ds_read_b128 v[168:171], v154 offset:3072
	ds_read_b128 v[172:175], v155
	ds_read_b128 v[176:179], v155 offset:1024
	ds_read_b128 v[180:183], v155 offset:2048
	ds_read_b128 v[184:187], v155 offset:3072
	s_add_u32 s28, s28, 0x40000
	s_addc_u32 s29, s29, 0
	s_mov_b32 m0, s40
	v_lshl_add_u64 v[226:227], s[28:29], 0, v[136:137]
	ds_read_b128 v[188:191], v151 offset:32768
	ds_read_b128 v[192:195], v151 offset:33792
	ds_read_b128 v[196:199], v151 offset:34816
	ds_read_b128 v[200:203], v151 offset:35840
	ds_read_b128 v[204:207], v151 offset:36864
	ds_read_b128 v[208:211], v151 offset:37888
	ds_read_b128 v[212:215], v151 offset:38912
	ds_read_b128 v[216:219], v151 offset:39936
	global_load_lds_dwordx4 v[226:227], off
	v_lshl_add_u64 v[226:227], s[28:29], 0, v[132:133]
	s_mov_b32 m0, s41
	s_nop 0
	global_load_lds_dwordx4 v[226:227], off
	s_cmp_lg_u32 s57, 12
	s_cbranch_scc1 .Lss_pf_skip_b
	v_lshl_add_u32 v244, s6, 8, v1
	v_ashrrev_i32_e32 v245, 31, v244
	v_lshlrev_b64 v[244:245], 6, v[244:245]
	v_lshl_add_u64 v[244:245], s[10:11], 0, v[244:245]
	global_load_dwordx4 v[228:231], v[244:245], off
	global_load_dwordx4 v[232:235], v[244:245], off offset:16
	global_load_dwordx4 v[236:239], v[244:245], off offset:32
	global_load_dwordx4 v[240:243], v[244:245], off offset:48

.LBB0_2432:
	v_lshl_add_u32 v146, s6, 8, v1
	v_ashrrev_i32_e32 v147, 31, v146
	v_lshlrev_b64 v[156:157], 6, v[146:147]
	v_lshl_add_u64 v[168:169], s[10:11], 0, v[156:157]
	v_mov_b64_e32 v[208:209], v[168:169]
	s_movk_i32 s98, 0x2000
	s_mov_b32 s99, 0
	v_lshl_add_u64 v[210:211], v[208:209], 0, s[98:99]
	global_load_dwordx4 v[192:195], v[208:209], off offset:1024
	global_load_dwordx4 v[196:199], v[208:209], off offset:1040
	global_load_dwordx4 v[200:203], v[208:209], off offset:1056
	global_load_dwordx4 v[204:207], v[208:209], off offset:1072
	global_load_dwordx4 v[176:179], v[208:209], off offset:2048
	global_load_dwordx4 v[180:183], v[208:209], off offset:2064
	global_load_dwordx4 v[184:187], v[208:209], off offset:2080
	global_load_dwordx4 v[188:191], v[208:209], off offset:2096
	v_mov_b32_e32 v174, v126
	v_mov_b32_e32 v175, v122
	v_mov_b32_e32 v122, v127
	v_mov_b32_e32 v126, v128
	v_mov_b32_e32 v127, v124
	v_mov_b32_e32 v124, v129
	v_mov_b32_e32 v128, v118
	v_mov_b32_e32 v129, v114
	v_mov_b32_e32 v114, v119
	v_lshl_or_b32 v172, s7, 7, v148
	v_ashrrev_i32_e32 v173, 31, v172
	s_waitcnt vmcnt(8)
	v_mov_b32_e32 v156, v228
	v_mov_b32_e32 v157, v229
	v_mov_b32_e32 v158, v230
	v_mov_b32_e32 v159, v231
	v_mov_b32_e32 v160, v232
	v_mov_b32_e32 v161, v233
	v_mov_b32_e32 v162, v234
	v_mov_b32_e32 v163, v235
	v_mov_b32_e32 v164, v236
	v_mov_b32_e32 v165, v237
	v_mov_b32_e32 v166, v238
	v_mov_b32_e32 v167, v239
	v_mov_b32_e32 v168, v240
	v_mov_b32_e32 v169, v241
	v_mov_b32_e32 v170, v242
	v_mov_b32_e32 v171, v243
	v_mov_b32_e32 v118, v157
	v_mov_b32_e32 v119, v158
	v_mov_b32_e32 v157, v159
	v_mov_b32_e32 v158, v161
	v_mov_b32_e32 v159, v162
	v_mov_b32_e32 v161, v163
	v_pk_add_f32 v[118:119], v[118:119], v[156:157]
	v_pk_add_f32 v[156:157], v[158:159], v[160:161]
	v_pk_add_f32 v[118:119], v[118:119], v[118:119] op_sel:[0,1] op_sel_hi:[1,0]
	v_pk_add_f32 v[156:157], v[156:157], v[156:157] op_sel:[0,1] op_sel_hi:[1,0]
	v_add_f32_e32 v162, v164, v165
	v_add_f32_e32 v164, v166, v167
	v_mov_b32_e32 v163, v170
	v_mov_b32_e32 v165, v171
	v_mov_b32_e32 v119, v168
	v_mov_b32_e32 v157, v169
	v_pk_add_f32 v[158:159], v[162:163], v[164:165]
	v_pk_add_f32 v[118:119], v[118:119], v[156:157]
	s_nop 0
	v_pk_add_f32 v[118:119], v[118:119], v[158:159]
	s_nop 0
	v_add_f32_e32 v118, v118, v119
	v_fmamk_f32 v118, v118, 0x3a800000, v152
	v_mul_f32_e32 v119, 0x4f800000, v118
	v_cmp_gt_f32_e32 vcc, s49, v118
	s_nop 1
	v_cndmask_b32_e32 v147, v118, v119, vcc
	v_sqrt_f32_e32 v156, v147
	v_mov_b32_e32 v118, v120
	v_mov_b32_e32 v119, v116
	v_mov_b32_e32 v116, v121
	v_add_u32_e32 v120, -1, v156
	v_add_u32_e32 v121, 1, v156
	v_fma_f32 v157, -v120, v156, v147
	v_fma_f32 v158, -v121, v156, v147
	v_cmp_ge_f32_e64 s[6:7], 0, v157
	s_nop 1
	v_cndmask_b32_e64 v120, v156, v120, s[6:7]
	v_cmp_lt_f32_e64 s[6:7], 0, v158
	s_nop 1
	v_cndmask_b32_e64 v120, v120, v121, s[6:7]
	v_mul_f32_e32 v121, 0x37800000, v120
	v_cndmask_b32_e32 v120, v120, v121, vcc
	v_cmp_class_f32_e32 vcc, v147, v153
	s_nop 1
	v_cndmask_b32_e32 v120, v120, v147, vcc
	v_div_scale_f32 v121, s[6:7], v120, v120, 1.0
	v_rcp_f32_e32 v147, v121
	v_div_scale_f32 v156, vcc, 1.0, v120, 1.0
	v_fma_f32 v157, -v121, v147, 1.0
	v_fmac_f32_e32 v147, v157, v147
	v_mul_f32_e32 v157, v156, v147
	v_fma_f32 v158, -v121, v157, v156
	v_fmac_f32_e32 v157, v158, v147
	v_fma_f32 v121, -v121, v157, v156
	v_div_fmas_f32 v121, v121, v147, v157
	v_div_fixup_f32 v120, v121, v120, 1.0
	v_pk_mul_f32 v[156:157], v[174:175], v[120:121] op_sel_hi:[1,0]
	v_pk_mul_f32 v[122:123], v[122:123], v[120:121] op_sel_hi:[1,0]
	v_pk_mul_f32 v[114:115], v[114:115], v[120:121] op_sel_hi:[1,0]
	v_pk_mul_f32 v[118:119], v[118:119], v[120:121] op_sel_hi:[1,0]
	v_pk_mul_f32 v[126:127], v[126:127], v[120:121] op_sel_hi:[1,0]
	v_pk_mul_f32 v[124:125], v[124:125], v[120:121] op_sel_hi:[1,0]
	v_pk_mul_f32 v[128:129], v[128:129], v[120:121] op_sel_hi:[1,0]
	v_pk_mul_f32 v[116:117], v[116:117], v[120:121] op_sel_hi:[1,0]
	v_mul_f32_e32 v120, 0xbfb8aa3b, v157
	v_mul_f32_e32 v121, 0xbfb8aa3b, v123
	v_mul_f32_e32 v160, 0xbfb8aa3b, v115
	v_mul_f32_e32 v161, 0xbfb8aa3b, v119
	v_mul_f32_e32 v147, 0xbfb8aa3b, v127
	v_mul_f32_e32 v158, 0xbfb8aa3b, v125
	v_mul_f32_e32 v159, 0xbfb8aa3b, v129
	v_mul_f32_e32 v162, 0xbfb8aa3b, v117
	v_exp_f32_e32 v120, v120
	v_exp_f32_e32 v121, v121
	v_exp_f32_e32 v160, v160
	v_exp_f32_e32 v161, v161
	v_exp_f32_e32 v147, v147
	v_exp_f32_e32 v158, v158
	v_exp_f32_e32 v159, v159
	v_exp_f32_e32 v162, v162
	v_add_f32_e32 v120, 1.0, v120
	v_add_f32_e32 v121, 1.0, v121
	v_add_f32_e32 v160, 1.0, v160
	v_add_f32_e32 v161, 1.0, v161
	v_add_f32_e32 v147, 1.0, v147
	v_add_f32_e32 v158, 1.0, v158
	v_add_f32_e32 v159, 1.0, v159
	v_add_f32_e32 v162, 1.0, v162
	v_rcp_f32_e32 v120, v120
	v_rcp_f32_e32 v121, v121
	v_rcp_f32_e32 v160, v160
	v_rcp_f32_e32 v161, v161
	v_rcp_f32_e32 v147, v147
	v_rcp_f32_e32 v158, v158
	v_rcp_f32_e32 v159, v159
	v_rcp_f32_e32 v162, v162
	v_mul_f32_e32 v120, v157, v120
	v_mul_f32_e32 v121, v123, v121
	v_mul_f32_e32 v115, v115, v160
	v_mul_f32_e32 v119, v119, v161
	v_mul_f32_e32 v123, v127, v147
	v_mul_f32_e32 v125, v125, v158
	v_mul_f32_e32 v127, v129, v159
	v_mul_f32_e32 v117, v117, v162
	v_mul_f32_e32 v120, v156, v120
	v_mul_f32_e32 v121, v122, v121
	v_mul_f32_e32 v114, v114, v115
	v_mul_f32_e32 v115, v118, v119
	v_mul_f32_e32 v122, v126, v123
	v_mul_f32_e32 v123, v124, v125
	v_mul_f32_e32 v124, v128, v127
	v_mul_f32_e32 v116, v116, v117
	v_cvt_pk_bf16_f32 v118, v120, v121
	v_cvt_pk_bf16_f32 v119, v122, v123
	v_cvt_pk_bf16_f32 v120, v124, v114
	v_cvt_pk_bf16_f32 v121, v115, v116
	v_mov_b64_e32 v[114:115], s[8:9]
	v_mad_i64_i32 v[122:123], s[6:7], v146, s50, v[114:115]
	v_lshlrev_b64 v[116:117], 1, v[172:173]
	v_lshl_add_u64 v[122:123], v[122:123], 0, v[116:117]
	global_store_dwordx4 v[122:123], v[118:121], off nt
	s_nop 1
	v_or_b32_e32 v118, 16, v146
	v_ashrrev_i32_e32 v119, 31, v118
	v_lshlrev_b64 v[120:121], 6, v[118:119]
	v_lshl_add_u64 v[128:129], s[10:11], 0, v[120:121]
	s_waitcnt vmcnt(5)
	v_mov_b32_e32 v120, v192
	v_mov_b32_e32 v121, v193
	v_mov_b32_e32 v122, v194
	v_mov_b32_e32 v123, v195
	v_mov_b32_e32 v124, v196
	v_mov_b32_e32 v125, v197
	v_mov_b32_e32 v126, v198
	v_mov_b32_e32 v127, v199
	v_mov_b32_e32 v156, v200
	v_mov_b32_e32 v157, v201
	v_mov_b32_e32 v158, v202
	v_mov_b32_e32 v159, v203
	v_mov_b32_e32 v160, v204
	v_mov_b32_e32 v161, v205
	v_mov_b32_e32 v162, v206
	v_mov_b32_e32 v163, v207
	global_load_dwordx4 v[192:195], v[208:209], off offset:3072
	global_load_dwordx4 v[196:199], v[208:209], off offset:3088
	global_load_dwordx4 v[200:203], v[208:209], off offset:3104
	global_load_dwordx4 v[204:207], v[208:209], off offset:3120
	v_mov_b32_e32 v128, v110
	v_mov_b32_e32 v110, v112
	v_mov_b32_e32 v112, v98
	v_mov_b32_e32 v129, v106
	v_mov_b32_e32 v106, v111
	v_mov_b32_e32 v111, v108
	v_mov_b32_e32 v108, v113
	v_mov_b32_e32 v113, v102
	v_mov_b32_e32 v164, v121
	v_mov_b32_e32 v165, v122
	v_mov_b32_e32 v121, v123
	v_mov_b32_e32 v122, v125
	v_mov_b32_e32 v123, v126
	v_mov_b32_e32 v125, v127
	v_pk_add_f32 v[120:121], v[164:165], v[120:121]
	v_pk_add_f32 v[122:123], v[122:123], v[124:125]
	v_pk_add_f32 v[120:121], v[120:121], v[120:121] op_sel:[0,1] op_sel_hi:[1,0]
	v_pk_add_f32 v[122:123], v[122:123], v[122:123] op_sel:[0,1] op_sel_hi:[1,0]
	v_add_f32_e32 v126, v156, v157
	v_add_f32_e32 v156, v158, v159
	v_mov_b32_e32 v127, v162
	v_mov_b32_e32 v157, v163
	v_mov_b32_e32 v121, v160
	v_mov_b32_e32 v123, v161
	v_pk_add_f32 v[124:125], v[126:127], v[156:157]
	v_pk_add_f32 v[120:121], v[120:121], v[122:123]
	s_nop 0
	v_pk_add_f32 v[120:121], v[120:121], v[124:125]
	s_nop 0
	v_add_f32_e32 v98, v120, v121
	v_fmamk_f32 v98, v98, 0x3a800000, v152
	v_mul_f32_e32 v102, 0x4f800000, v98
	v_cmp_gt_f32_e32 vcc, s49, v98
	s_nop 1
	v_cndmask_b32_e32 v119, v98, v102, vcc
	v_sqrt_f32_e32 v120, v119
	v_mov_b32_e32 v98, v100
	v_mov_b32_e32 v102, v99
	v_mov_b32_e32 v99, v104
	v_add_u32_e32 v100, -1, v120
	v_add_u32_e32 v104, 1, v120
	v_fma_f32 v121, -v100, v120, v119
	v_fma_f32 v122, -v104, v120, v119
	v_cmp_ge_f32_e64 s[6:7], 0, v121
	s_nop 1
	v_cndmask_b32_e64 v100, v120, v100, s[6:7]
	v_cmp_lt_f32_e64 s[6:7], 0, v122
	s_nop 1
	v_cndmask_b32_e64 v100, v100, v104, s[6:7]
	v_mul_f32_e32 v104, 0x37800000, v100
	v_cndmask_b32_e32 v100, v100, v104, vcc
	v_cmp_class_f32_e32 vcc, v119, v153
	v_mov_b32_e32 v104, v101
	s_nop 0
	v_cndmask_b32_e32 v100, v100, v119, vcc
	v_div_scale_f32 v119, s[6:7], v100, v100, 1.0
	v_rcp_f32_e32 v120, v119
	v_div_scale_f32 v101, vcc, 1.0, v100, 1.0
	v_fma_f32 v121, -v119, v120, 1.0
	v_fmac_f32_e32 v120, v121, v120
	v_mul_f32_e32 v121, v101, v120
	v_fma_f32 v122, -v119, v121, v101
	v_fmac_f32_e32 v121, v122, v120
	v_fma_f32 v101, -v119, v121, v101
	v_div_fmas_f32 v101, v101, v120, v121
	v_div_fixup_f32 v100, v101, v100, 1.0
	v_pk_mul_f32 v[106:107], v[106:107], v[100:101] op_sel_hi:[1,0]
	v_pk_mul_f32 v[110:111], v[110:111], v[100:101] op_sel_hi:[1,0]
	v_pk_mul_f32 v[108:109], v[108:109], v[100:101] op_sel_hi:[1,0]
	v_pk_mul_f32 v[120:121], v[128:129], v[100:101] op_sel_hi:[1,0]
	v_pk_mul_f32 v[112:113], v[112:113], v[100:101] op_sel_hi:[1,0]
	v_pk_mul_f32 v[102:103], v[102:103], v[100:101] op_sel_hi:[1,0]
	v_pk_mul_f32 v[98:99], v[98:99], v[100:101] op_sel_hi:[1,0]
	v_pk_mul_f32 v[100:101], v[104:105], v[100:101] op_sel_hi:[1,0]
	v_mul_f32_e32 v105, 0xbfb8aa3b, v107
	v_mul_f32_e32 v119, 0xbfb8aa3b, v111
	v_mul_f32_e32 v122, 0xbfb8aa3b, v109
	v_exp_f32_e32 v105, v105
	v_exp_f32_e32 v119, v119
	v_exp_f32_e32 v122, v122
	v_mul_f32_e32 v124, 0xbfb8aa3b, v103
	v_mul_f32_e32 v125, 0xbfb8aa3b, v99
	v_mul_f32_e32 v126, 0xbfb8aa3b, v101
	v_exp_f32_e32 v124, v124
	v_exp_f32_e32 v125, v125
	v_add_f32_e32 v105, 1.0, v105
	v_add_f32_e32 v119, 1.0, v119
	v_add_f32_e32 v122, 1.0, v122
	v_mul_f32_e32 v104, 0xbfb8aa3b, v121
	v_mul_f32_e32 v123, 0xbfb8aa3b, v113
	v_exp_f32_e32 v126, v126
	v_rcp_f32_e32 v105, v105
	v_rcp_f32_e32 v119, v119
	v_rcp_f32_e32 v122, v122
	v_exp_f32_e32 v104, v104
	v_exp_f32_e32 v123, v123
	v_add_f32_e32 v124, 1.0, v124
	v_add_f32_e32 v125, 1.0, v125
	v_add_f32_e32 v126, 1.0, v126
	v_rcp_f32_e32 v124, v124
	v_rcp_f32_e32 v125, v125
	v_mul_f32_e32 v105, v107, v105
	v_mul_f32_e32 v107, v111, v119
	v_mul_f32_e32 v109, v109, v122
	v_add_f32_e32 v104, 1.0, v104
	v_add_f32_e32 v123, 1.0, v123
	v_mul_f32_e32 v105, v106, v105
	v_mul_f32_e32 v106, v110, v107
	v_mul_f32_e32 v107, v108, v109
	v_rcp_f32_e32 v109, v126
	v_rcp_f32_e32 v104, v104
	v_rcp_f32_e32 v123, v123
	v_mul_f32_e32 v103, v103, v124
	v_mul_f32_e32 v99, v99, v125
	v_mul_f32_e32 v102, v102, v103
	v_mul_f32_e32 v103, v98, v99
	v_mul_f32_e32 v98, v101, v109
	v_mul_f32_e32 v104, v121, v104
	v_mul_f32_e32 v111, v113, v123
	v_mul_f32_e32 v101, v100, v98
	v_mul_f32_e32 v104, v120, v104
	v_mul_f32_e32 v108, v112, v111
	v_cvt_pk_bf16_f32 v98, v104, v105
	v_cvt_pk_bf16_f32 v99, v106, v107
	v_cvt_pk_bf16_f32 v100, v108, v102
	v_cvt_pk_bf16_f32 v101, v103, v101
	v_mad_i64_i32 v[102:103], s[6:7], v118, s50, v[114:115]
	v_lshl_add_u64 v[102:103], v[102:103], 0, v[116:117]
	global_store_dwordx4 v[102:103], v[98:101], off nt
	s_nop 1
	v_or_b32_e32 v98, 32, v146
	v_ashrrev_i32_e32 v99, 31, v98
	v_lshlrev_b64 v[100:101], 6, v[98:99]
	v_lshl_add_u64 v[112:113], s[10:11], 0, v[100:101]
	s_waitcnt vmcnt(6)
	v_mov_b32_e32 v100, v176
	v_mov_b32_e32 v101, v177
	v_mov_b32_e32 v102, v178
	v_mov_b32_e32 v103, v179
	v_mov_b32_e32 v104, v180
	v_mov_b32_e32 v105, v181
	v_mov_b32_e32 v106, v182
	v_mov_b32_e32 v107, v183
	v_mov_b32_e32 v108, v184
	v_mov_b32_e32 v109, v185
	v_mov_b32_e32 v110, v186
	v_mov_b32_e32 v111, v187
	v_mov_b32_e32 v118, v188
	v_mov_b32_e32 v119, v189
	v_mov_b32_e32 v120, v190
	v_mov_b32_e32 v121, v191
	global_load_dwordx4 v[176:179], v[210:211], off
	global_load_dwordx4 v[180:183], v[210:211], off offset:16
	global_load_dwordx4 v[184:187], v[210:211], off offset:32
	global_load_dwordx4 v[188:191], v[210:211], off offset:48
	v_mov_b32_e32 v112, v94
	v_mov_b32_e32 v94, v96
	v_mov_b32_e32 v96, v82
	v_mov_b32_e32 v113, v90
	v_mov_b32_e32 v90, v95
	v_mov_b32_e32 v95, v92
	v_mov_b32_e32 v92, v97
	v_mov_b32_e32 v97, v86
	v_mov_b32_e32 v122, v101
	v_mov_b32_e32 v123, v102
	v_mov_b32_e32 v101, v103
	v_mov_b32_e32 v102, v105
	v_mov_b32_e32 v103, v106
	v_mov_b32_e32 v105, v107
	v_pk_add_f32 v[100:101], v[122:123], v[100:101]
	v_pk_add_f32 v[102:103], v[102:103], v[104:105]
	v_pk_add_f32 v[100:101], v[100:101], v[100:101] op_sel:[0,1] op_sel_hi:[1,0]
	v_pk_add_f32 v[102:103], v[102:103], v[102:103] op_sel:[0,1] op_sel_hi:[1,0]
	v_add_f32_e32 v106, v108, v109
	v_add_f32_e32 v108, v110, v111
	v_mov_b32_e32 v107, v120
	v_mov_b32_e32 v109, v121
	v_mov_b32_e32 v101, v118
	v_mov_b32_e32 v103, v119
	v_pk_add_f32 v[104:105], v[106:107], v[108:109]
	v_pk_add_f32 v[100:101], v[100:101], v[102:103]
	s_nop 0
	v_pk_add_f32 v[100:101], v[100:101], v[104:105]
	s_nop 0
	v_add_f32_e32 v82, v100, v101
	v_fmamk_f32 v82, v82, 0x3a800000, v152
	v_mul_f32_e32 v86, 0x4f800000, v82
	v_cmp_gt_f32_e32 vcc, s49, v82
	s_nop 1
	v_cndmask_b32_e32 v99, v82, v86, vcc
	v_sqrt_f32_e32 v100, v99
	v_mov_b32_e32 v82, v84
	v_mov_b32_e32 v86, v83
	v_mov_b32_e32 v83, v88
	v_add_u32_e32 v84, -1, v100
	v_add_u32_e32 v88, 1, v100
	v_fma_f32 v101, -v84, v100, v99
	v_fma_f32 v102, -v88, v100, v99
	v_cmp_ge_f32_e64 s[6:7], 0, v101
	s_nop 1
	v_cndmask_b32_e64 v84, v100, v84, s[6:7]
	v_cmp_lt_f32_e64 s[6:7], 0, v102
	s_nop 1
	v_cndmask_b32_e64 v84, v84, v88, s[6:7]
	v_mul_f32_e32 v88, 0x37800000, v84
	v_cndmask_b32_e32 v84, v84, v88, vcc
	v_cmp_class_f32_e32 vcc, v99, v153
	v_mov_b32_e32 v88, v85
	s_nop 0
	v_cndmask_b32_e32 v84, v84, v99, vcc
	v_div_scale_f32 v99, s[6:7], v84, v84, 1.0
	v_rcp_f32_e32 v100, v99
	v_div_scale_f32 v85, vcc, 1.0, v84, 1.0
	v_fma_f32 v101, -v99, v100, 1.0
	v_fmac_f32_e32 v100, v101, v100
	v_mul_f32_e32 v101, v85, v100
	v_fma_f32 v102, -v99, v101, v85
	v_fmac_f32_e32 v101, v102, v100
	v_fma_f32 v85, -v99, v101, v85
	v_div_fmas_f32 v85, v85, v100, v101
	v_div_fixup_f32 v84, v85, v84, 1.0
	v_pk_mul_f32 v[90:91], v[90:91], v[84:85] op_sel_hi:[1,0]
	v_pk_mul_f32 v[94:95], v[94:95], v[84:85] op_sel_hi:[1,0]
	v_pk_mul_f32 v[92:93], v[92:93], v[84:85] op_sel_hi:[1,0]
	v_pk_mul_f32 v[100:101], v[112:113], v[84:85] op_sel_hi:[1,0]
	v_pk_mul_f32 v[96:97], v[96:97], v[84:85] op_sel_hi:[1,0]
	v_pk_mul_f32 v[86:87], v[86:87], v[84:85] op_sel_hi:[1,0]
	v_pk_mul_f32 v[82:83], v[82:83], v[84:85] op_sel_hi:[1,0]
	v_pk_mul_f32 v[84:85], v[88:89], v[84:85] op_sel_hi:[1,0]
	v_mul_f32_e32 v89, 0xbfb8aa3b, v91
	v_mul_f32_e32 v99, 0xbfb8aa3b, v95
	v_mul_f32_e32 v102, 0xbfb8aa3b, v93
	v_exp_f32_e32 v89, v89
	v_exp_f32_e32 v99, v99
	v_exp_f32_e32 v102, v102
	v_mul_f32_e32 v104, 0xbfb8aa3b, v87
	v_add_f32_e32 v89, 1.0, v89
	v_add_f32_e32 v99, 1.0, v99
	v_add_f32_e32 v102, 1.0, v102
	v_rcp_f32_e32 v89, v89
	v_rcp_f32_e32 v99, v99
	v_rcp_f32_e32 v102, v102
	v_mul_f32_e32 v105, 0xbfb8aa3b, v83
	v_mul_f32_e32 v89, v91, v89
	v_mul_f32_e32 v91, v95, v99
	v_mul_f32_e32 v93, v93, v102
	v_exp_f32_e32 v104, v104
	v_exp_f32_e32 v105, v105
	v_mul_f32_e32 v89, v90, v89
	v_mul_f32_e32 v90, v94, v91
	v_mul_f32_e32 v91, v92, v93
	v_mul_f32_e32 v93, 0xbfb8aa3b, v85
	v_mul_f32_e32 v88, 0xbfb8aa3b, v101
	v_mul_f32_e32 v103, 0xbfb8aa3b, v97
	v_exp_f32_e32 v93, v93
	v_exp_f32_e32 v88, v88
	v_exp_f32_e32 v103, v103
	v_add_f32_e32 v104, 1.0, v104
	v_add_f32_e32 v94, 1.0, v105
	v_rcp_f32_e32 v104, v104
	v_rcp_f32_e32 v94, v94
	v_add_f32_e32 v93, 1.0, v93
	v_add_f32_e32 v88, 1.0, v88
	v_add_f32_e32 v103, 1.0, v103
	v_rcp_f32_e32 v93, v93
	v_rcp_f32_e32 v88, v88
	v_rcp_f32_e32 v103, v103
	v_mul_f32_e32 v87, v87, v104
	v_mul_f32_e32 v83, v83, v94
	v_mul_f32_e32 v86, v86, v87
	v_mul_f32_e32 v87, v82, v83
	v_mul_f32_e32 v82, v85, v93
	v_mul_f32_e32 v88, v101, v88
	v_mul_f32_e32 v95, v97, v103
	v_mul_f32_e32 v85, v84, v82
	v_mul_f32_e32 v88, v100, v88
	v_mul_f32_e32 v92, v96, v95
	v_cvt_pk_bf16_f32 v82, v88, v89
	v_cvt_pk_bf16_f32 v83, v90, v91
	v_cvt_pk_bf16_f32 v84, v92, v86
	v_cvt_pk_bf16_f32 v85, v87, v85
	v_mad_i64_i32 v[86:87], s[6:7], v98, s50, v[114:115]
	v_lshl_add_u64 v[86:87], v[86:87], 0, v[116:117]
	global_store_dwordx4 v[86:87], v[82:85], off nt
	v_mov_b32_e32 v100, v78
	v_mov_b32_e32 v101, v74
	v_or_b32_e32 v82, 48, v146
	v_ashrrev_i32_e32 v83, 31, v82
	v_lshlrev_b64 v[84:85], 6, v[82:83]
	v_lshl_add_u64 v[96:97], s[10:11], 0, v[84:85]
	s_waitcnt vmcnt(6)
	v_mov_b32_e32 v84, v192
	v_mov_b32_e32 v85, v193
	v_mov_b32_e32 v86, v194
	v_mov_b32_e32 v87, v195
	v_mov_b32_e32 v88, v196
	v_mov_b32_e32 v89, v197
	v_mov_b32_e32 v90, v198
	v_mov_b32_e32 v91, v199
	v_mov_b32_e32 v92, v200
	v_mov_b32_e32 v93, v201
	v_mov_b32_e32 v94, v202
	v_mov_b32_e32 v95, v203
	v_mov_b32_e32 v96, v204
	v_mov_b32_e32 v97, v205
	v_mov_b32_e32 v98, v206
	v_mov_b32_e32 v99, v207
	global_load_dwordx4 v[192:195], v[210:211], off offset:1024
	global_load_dwordx4 v[196:199], v[210:211], off offset:1040
	global_load_dwordx4 v[200:203], v[210:211], off offset:1056
	global_load_dwordx4 v[204:207], v[210:211], off offset:1072
	v_mov_b32_e32 v74, v79
	v_mov_b32_e32 v78, v80
	v_mov_b32_e32 v79, v76
	v_mov_b32_e32 v76, v81
	v_mov_b32_e32 v80, v85
	v_mov_b32_e32 v81, v86
	v_mov_b32_e32 v85, v87
	v_mov_b32_e32 v86, v89
	v_mov_b32_e32 v87, v90
	v_mov_b32_e32 v89, v91
	v_pk_add_f32 v[80:81], v[80:81], v[84:85]
	v_pk_add_f32 v[84:85], v[86:87], v[88:89]
	v_pk_add_f32 v[80:81], v[80:81], v[80:81] op_sel:[0,1] op_sel_hi:[1,0]
	v_pk_add_f32 v[84:85], v[84:85], v[84:85] op_sel:[0,1] op_sel_hi:[1,0]
	v_add_f32_e32 v90, v92, v93
	v_add_f32_e32 v92, v94, v95
	v_mov_b32_e32 v91, v98
	v_mov_b32_e32 v93, v99
	v_mov_b32_e32 v81, v96
	v_mov_b32_e32 v85, v97
	v_pk_add_f32 v[86:87], v[90:91], v[92:93]
	v_pk_add_f32 v[80:81], v[80:81], v[84:85]
	s_nop 0
	v_pk_add_f32 v[80:81], v[80:81], v[86:87]
	s_nop 0
	v_add_f32_e32 v80, v80, v81
	v_fmamk_f32 v80, v80, 0x3a800000, v152
	v_mul_f32_e32 v81, 0x4f800000, v80
	v_cmp_gt_f32_e32 vcc, s49, v80
	s_nop 1
	v_cndmask_b32_e32 v83, v80, v81, vcc
	v_sqrt_f32_e32 v84, v83
	v_mov_b32_e32 v80, v66
	v_mov_b32_e32 v81, v70
	v_mov_b32_e32 v70, v67
	v_add_u32_e32 v66, -1, v84
	v_add_u32_e32 v67, 1, v84
	v_fma_f32 v85, -v66, v84, v83
	v_fma_f32 v86, -v67, v84, v83
	v_cmp_ge_f32_e64 s[6:7], 0, v85
	s_nop 1
	v_cndmask_b32_e64 v66, v84, v66, s[6:7]
	v_cmp_lt_f32_e64 s[6:7], 0, v86
	s_nop 1
	v_cndmask_b32_e64 v66, v66, v67, s[6:7]
	v_mul_f32_e32 v67, 0x37800000, v66
	v_cndmask_b32_e32 v66, v66, v67, vcc
	v_cmp_class_f32_e32 vcc, v83, v153
	s_nop 1
	v_cndmask_b32_e32 v67, v66, v83, vcc
	v_div_scale_f32 v83, s[6:7], v67, v67, 1.0
	v_rcp_f32_e32 v84, v83
	v_mov_b32_e32 v66, v68
	v_div_scale_f32 v68, vcc, 1.0, v67, 1.0
	v_fma_f32 v85, -v83, v84, 1.0
	v_fmac_f32_e32 v84, v85, v84
	v_mul_f32_e32 v85, v68, v84
	v_fma_f32 v86, -v83, v85, v68
	v_fmac_f32_e32 v85, v86, v84
	v_fma_f32 v68, -v83, v85, v68
	v_div_fmas_f32 v68, v68, v84, v85
	v_div_fixup_f32 v68, v68, v67, 1.0
	v_pk_mul_f32 v[84:85], v[100:101], v[68:69] op_sel_hi:[1,0]
	v_pk_mul_f32 v[74:75], v[74:75], v[68:69] op_sel_hi:[1,0]
	v_mul_f32_e32 v67, 0xbfb8aa3b, v85
	v_mul_f32_e32 v83, 0xbfb8aa3b, v75
	v_exp_f32_e32 v67, v67
	v_pk_mul_f32 v[78:79], v[78:79], v[68:69] op_sel_hi:[1,0]
	v_exp_f32_e32 v83, v83
	v_mul_f32_e32 v86, 0xbfb8aa3b, v79
	v_exp_f32_e32 v86, v86
	v_add_f32_e32 v67, 1.0, v67
	v_add_f32_e32 v83, 1.0, v83
	v_rcp_f32_e32 v67, v67
	v_rcp_f32_e32 v83, v83
	v_add_f32_e32 v86, 1.0, v86
	v_rcp_f32_e32 v86, v86
	v_mul_f32_e32 v67, v85, v67
	v_mul_f32_e32 v75, v75, v83
	v_mul_f32_e32 v83, v84, v67
	v_mov_b32_e32 v67, v72
	v_pk_mul_f32 v[66:67], v[66:67], v[68:69] op_sel_hi:[1,0]
	v_mul_f32_e32 v79, v79, v86
	v_mul_f32_e32 v72, 0xbfb8aa3b, v67
	v_pk_mul_f32 v[70:71], v[70:71], v[68:69] op_sel_hi:[1,0]
	v_mul_f32_e32 v74, v74, v75
	v_mul_f32_e32 v75, v78, v79
	v_exp_f32_e32 v78, v72
	v_mov_b32_e32 v72, v69
	v_pk_mul_f32 v[76:77], v[76:77], v[68:69] op_sel_hi:[1,0]
	v_pk_mul_f32 v[80:81], v[80:81], v[68:69] op_sel_hi:[1,0]
	v_mul_f32_e32 v89, 0xbfb8aa3b, v71
	v_pk_mul_f32 v[68:69], v[72:73], v[68:69] op_sel_hi:[1,0]
	v_exp_f32_e32 v89, v89
	v_mul_f32_e32 v72, 0xbfb8aa3b, v69
	v_mul_f32_e32 v87, 0xbfb8aa3b, v77
	v_mul_f32_e32 v88, 0xbfb8aa3b, v81
	v_exp_f32_e32 v72, v72
	v_exp_f32_e32 v87, v87
	v_exp_f32_e32 v88, v88
	v_add_f32_e32 v89, 1.0, v89
	v_add_f32_e32 v73, 1.0, v78
	v_rcp_f32_e32 v89, v89
	v_rcp_f32_e32 v73, v73
	v_add_f32_e32 v72, 1.0, v72
	v_add_f32_e32 v87, 1.0, v87
	v_add_f32_e32 v88, 1.0, v88
	v_rcp_f32_e32 v72, v72
	v_rcp_f32_e32 v87, v87
	v_rcp_f32_e32 v88, v88
	v_mul_f32_e32 v71, v71, v89
	v_mul_f32_e32 v67, v67, v73
	v_mul_f32_e32 v70, v70, v71
	v_mul_f32_e32 v71, v66, v67
	v_mul_f32_e32 v66, v69, v72
	v_mul_f32_e32 v77, v77, v87
	v_mul_f32_e32 v81, v81, v88
	v_mul_f32_e32 v69, v68, v66
	v_mul_f32_e32 v76, v76, v77
	v_mul_f32_e32 v77, v80, v81
	v_cvt_pk_bf16_f32 v66, v83, v74
	v_cvt_pk_bf16_f32 v67, v75, v76
	v_cvt_pk_bf16_f32 v68, v77, v70
	v_cvt_pk_bf16_f32 v69, v71, v69
	v_mad_i64_i32 v[70:71], s[6:7], v82, s50, v[114:115]
	v_lshl_add_u64 v[70:71], v[70:71], 0, v[116:117]
	global_store_dwordx4 v[70:71], v[66:69], off nt
	v_mov_b32_e32 v85, v58
	v_mov_b32_e32 v58, v63
	v_add_u32_e32 v66, 0x80, v146
	v_ashrrev_i32_e32 v67, 31, v66
	v_lshlrev_b64 v[68:69], 6, v[66:67]
	v_lshl_add_u64 v[80:81], s[10:11], 0, v[68:69]
	s_waitcnt vmcnt(6)
	v_mov_b32_e32 v68, v176
	v_mov_b32_e32 v69, v177
	v_mov_b32_e32 v70, v178
	v_mov_b32_e32 v71, v179
	v_mov_b32_e32 v72, v180
	v_mov_b32_e32 v73, v181
	v_mov_b32_e32 v74, v182
	v_mov_b32_e32 v75, v183
	v_mov_b32_e32 v76, v184
	v_mov_b32_e32 v77, v185
	v_mov_b32_e32 v78, v186
	v_mov_b32_e32 v79, v187
	v_mov_b32_e32 v80, v188
	v_mov_b32_e32 v81, v189
	v_mov_b32_e32 v82, v190
	v_mov_b32_e32 v83, v191
	global_load_dwordx4 v[176:179], v[210:211], off offset:2048
	global_load_dwordx4 v[180:183], v[210:211], off offset:2064
	global_load_dwordx4 v[184:187], v[210:211], off offset:2080
	global_load_dwordx4 v[188:191], v[210:211], off offset:2096
	v_mov_b32_e32 v63, v60
	v_mov_b32_e32 v84, v62
	v_mov_b32_e32 v62, v64
	v_mov_b32_e32 v86, v69
	v_mov_b32_e32 v87, v70
	v_mov_b32_e32 v69, v71
	v_mov_b32_e32 v70, v73
	v_mov_b32_e32 v71, v74
	v_mov_b32_e32 v73, v75
	v_pk_add_f32 v[68:69], v[86:87], v[68:69]
	v_pk_add_f32 v[70:71], v[70:71], v[72:73]
	v_pk_add_f32 v[68:69], v[68:69], v[68:69] op_sel:[0,1] op_sel_hi:[1,0]
	v_pk_add_f32 v[70:71], v[70:71], v[70:71] op_sel:[0,1] op_sel_hi:[1,0]
	v_add_f32_e32 v74, v76, v77
	v_add_f32_e32 v76, v78, v79
	v_mov_b32_e32 v75, v82
	v_mov_b32_e32 v77, v83
	v_mov_b32_e32 v69, v80
	v_mov_b32_e32 v71, v81
	v_pk_add_f32 v[72:73], v[74:75], v[76:77]
	v_pk_add_f32 v[68:69], v[68:69], v[70:71]
	s_nop 0
	v_pk_add_f32 v[68:69], v[68:69], v[72:73]
	s_nop 0
	v_add_f32_e32 v60, v68, v69
	v_fmamk_f32 v60, v60, 0x3a800000, v152
	v_mul_f32_e32 v64, 0x4f800000, v60
	v_cmp_gt_f32_e32 vcc, s49, v60
	s_nop 1
	v_cndmask_b32_e32 v67, v60, v64, vcc
	v_sqrt_f32_e32 v68, v67
	v_mov_b32_e32 v64, v50
	v_mov_b32_e32 v60, v65
	v_mov_b32_e32 v65, v54
	v_add_u32_e32 v50, -1, v68
	v_add_u32_e32 v54, 1, v68
	v_fma_f32 v69, -v50, v68, v67
	v_fma_f32 v70, -v54, v68, v67
	v_cmp_ge_f32_e64 s[6:7], 0, v69
	s_nop 1
	v_cndmask_b32_e64 v50, v68, v50, s[6:7]
	v_cmp_lt_f32_e64 s[6:7], 0, v70
	s_nop 1
	v_cndmask_b32_e64 v50, v50, v54, s[6:7]
	v_mul_f32_e32 v54, 0x37800000, v50
	v_cndmask_b32_e32 v50, v50, v54, vcc
	v_cmp_class_f32_e32 vcc, v67, v153
	v_mov_b32_e32 v54, v51
	s_nop 0
	v_cndmask_b32_e32 v50, v50, v67, vcc
	v_div_scale_f32 v67, s[6:7], v50, v50, 1.0
	v_rcp_f32_e32 v68, v67
	v_div_scale_f32 v51, vcc, 1.0, v50, 1.0
	v_fma_f32 v69, -v67, v68, 1.0
	v_fmac_f32_e32 v68, v69, v68
	v_mul_f32_e32 v69, v51, v68
	v_fma_f32 v70, -v67, v69, v51
	v_fmac_f32_e32 v69, v70, v68
	v_fma_f32 v51, -v67, v69, v51
	v_div_fmas_f32 v51, v51, v68, v69
	v_div_fixup_f32 v50, v51, v50, 1.0
	v_pk_mul_f32 v[68:69], v[84:85], v[50:51] op_sel_hi:[1,0]
	v_pk_mul_f32 v[58:59], v[58:59], v[50:51] op_sel_hi:[1,0]
	v_pk_mul_f32 v[62:63], v[62:63], v[50:51] op_sel_hi:[1,0]
	v_pk_mul_f32 v[60:61], v[60:61], v[50:51] op_sel_hi:[1,0]
	v_pk_mul_f32 v[64:65], v[64:65], v[50:51] op_sel_hi:[1,0]
	v_pk_mul_f32 v[54:55], v[54:55], v[50:51] op_sel_hi:[1,0]
	v_mul_f32_e32 v51, 0xbfb8aa3b, v69
	v_mul_f32_e32 v67, 0xbfb8aa3b, v59
	v_mul_f32_e32 v71, 0xbfb8aa3b, v61
	v_mul_f32_e32 v72, 0xbfb8aa3b, v65
	v_exp_f32_e32 v51, v51
	v_exp_f32_e32 v67, v67
	v_exp_f32_e32 v71, v71
	v_exp_f32_e32 v72, v72
	v_mul_f32_e32 v70, 0xbfb8aa3b, v63
	v_exp_f32_e32 v70, v70
	v_add_f32_e32 v51, 1.0, v51
	v_add_f32_e32 v67, 1.0, v67
	v_add_f32_e32 v71, 1.0, v71
	v_add_f32_e32 v72, 1.0, v72
	v_rcp_f32_e32 v51, v51
	v_mul_f32_e32 v73, 0xbfb8aa3b, v55
	v_rcp_f32_e32 v67, v67
	v_rcp_f32_e32 v71, v71
	v_rcp_f32_e32 v72, v72
	v_exp_f32_e32 v73, v73
	v_add_f32_e32 v70, 1.0, v70
	v_rcp_f32_e32 v70, v70
	v_mul_f32_e32 v51, v69, v51
	v_mul_f32_e32 v59, v59, v67
	v_mul_f32_e32 v61, v61, v71
	v_mul_f32_e32 v67, v68, v51
	v_mul_f32_e32 v51, v65, v72
	v_mul_f32_e32 v68, v58, v59
	v_mul_f32_e32 v60, v60, v61
	v_mul_f32_e32 v61, v64, v51
	v_add_f32_e32 v51, 1.0, v73
	v_mov_b32_e32 v58, v52
	v_mov_b32_e32 v59, v56
	v_mul_f32_e32 v63, v63, v70
	v_pk_mul_f32 v[58:59], v[58:59], v[50:51] op_sel_hi:[1,0]
	v_mul_f32_e32 v62, v62, v63
	v_rcp_f32_e32 v63, v51
	v_mul_f32_e32 v51, 0xbfb8aa3b, v59
	v_mov_b32_e32 v56, v53
	v_exp_f32_e32 v52, v51
	v_pk_mul_f32 v[50:51], v[56:57], v[50:51] op_sel_hi:[1,0]
	v_mul_f32_e32 v55, v55, v63
	v_mul_f32_e32 v53, 0xbfb8aa3b, v51
	v_exp_f32_e32 v53, v53
	v_add_f32_e32 v52, 1.0, v52
	v_rcp_f32_e32 v52, v52
	v_mul_f32_e32 v54, v54, v55
	v_add_f32_e32 v53, 1.0, v53
	v_rcp_f32_e32 v53, v53
	v_mul_f32_e32 v52, v59, v52
	v_mul_f32_e32 v55, v58, v52
	v_mov_b32_e32 v69, v42
	v_mul_f32_e32 v51, v51, v53
	v_mul_f32_e32 v53, v50, v51
	v_cvt_pk_bf16_f32 v50, v67, v68
	v_cvt_pk_bf16_f32 v51, v62, v60
	v_cvt_pk_bf16_f32 v52, v61, v54
	v_cvt_pk_bf16_f32 v53, v55, v53
	v_mad_i64_i32 v[54:55], s[6:7], v66, s50, v[114:115]
	v_add_u32_e32 v66, 0x90, v146
	v_lshl_add_u64 v[54:55], v[54:55], 0, v[116:117]
	v_ashrrev_i32_e32 v67, 31, v66
	global_store_dwordx4 v[54:55], v[50:53], off nt
	v_mov_b32_e32 v42, v47
	v_mov_b32_e32 v68, v46
	v_lshlrev_b64 v[50:51], 6, v[66:67]
	v_lshl_add_u64 v[62:63], s[10:11], 0, v[50:51]
	s_waitcnt vmcnt(6)
	v_mov_b32_e32 v50, v192
	v_mov_b32_e32 v51, v193
	v_mov_b32_e32 v52, v194
	v_mov_b32_e32 v53, v195
	v_mov_b32_e32 v54, v196
	v_mov_b32_e32 v55, v197
	v_mov_b32_e32 v56, v198
	v_mov_b32_e32 v57, v199
	v_mov_b32_e32 v58, v200
	v_mov_b32_e32 v59, v201
	v_mov_b32_e32 v60, v202
	v_mov_b32_e32 v61, v203
	v_mov_b32_e32 v62, v204
	v_mov_b32_e32 v63, v205
	v_mov_b32_e32 v64, v206
	v_mov_b32_e32 v65, v207
	global_load_dwordx4 v[192:195], v[210:211], off offset:3072
	global_load_dwordx4 v[196:199], v[210:211], off offset:3088
	global_load_dwordx4 v[200:203], v[210:211], off offset:3104
	global_load_dwordx4 v[204:207], v[210:211], off offset:3120
	v_mov_b32_e32 v46, v48
	v_mov_b32_e32 v70, v51
	v_mov_b32_e32 v71, v52
	v_mov_b32_e32 v51, v53
	v_mov_b32_e32 v52, v55
	v_mov_b32_e32 v53, v56
	v_mov_b32_e32 v55, v57
	v_pk_add_f32 v[50:51], v[70:71], v[50:51]
	v_pk_add_f32 v[52:53], v[52:53], v[54:55]
	v_pk_add_f32 v[50:51], v[50:51], v[50:51] op_sel:[0,1] op_sel_hi:[1,0]
	v_pk_add_f32 v[52:53], v[52:53], v[52:53] op_sel:[0,1] op_sel_hi:[1,0]
	v_add_f32_e32 v56, v58, v59
	v_add_f32_e32 v58, v60, v61
	v_mov_b32_e32 v57, v64
	v_mov_b32_e32 v59, v65
	v_mov_b32_e32 v51, v62
	v_mov_b32_e32 v53, v63
	v_pk_add_f32 v[54:55], v[56:57], v[58:59]
	v_pk_add_f32 v[50:51], v[50:51], v[52:53]
	s_nop 0
	v_pk_add_f32 v[50:51], v[50:51], v[54:55]
	s_nop 0
	v_add_f32_e32 v47, v50, v51
	v_fmamk_f32 v47, v47, 0x3a800000, v152
	v_mul_f32_e32 v48, 0x4f800000, v47
	v_cmp_gt_f32_e32 vcc, s49, v47
	s_nop 1
	v_cndmask_b32_e32 v50, v47, v48, vcc
	v_sqrt_f32_e32 v51, v50
	v_mov_b32_e32 v48, v34
	v_mov_b32_e32 v47, v44
	v_mov_b32_e32 v44, v49
	v_add_u32_e32 v34, -1, v51
	v_add_u32_e32 v49, 1, v51
	v_fma_f32 v52, -v34, v51, v50
	v_fma_f32 v53, -v49, v51, v50
	v_cmp_ge_f32_e64 s[6:7], 0, v52
	s_nop 1
	v_cndmask_b32_e64 v34, v51, v34, s[6:7]
	v_cmp_lt_f32_e64 s[6:7], 0, v53
	s_nop 1
	v_cndmask_b32_e64 v34, v34, v49, s[6:7]
	v_mul_f32_e32 v49, 0x37800000, v34
	v_cndmask_b32_e32 v34, v34, v49, vcc
	v_cmp_class_f32_e32 vcc, v50, v153
	v_mov_b32_e32 v49, v38
	s_nop 0
	v_cndmask_b32_e32 v34, v34, v50, vcc
	v_div_scale_f32 v50, s[6:7], v34, v34, 1.0
	v_rcp_f32_e32 v51, v50
	v_div_scale_f32 v38, vcc, 1.0, v34, 1.0
	v_fma_f32 v52, -v50, v51, 1.0
	v_fmac_f32_e32 v51, v52, v51
	v_mul_f32_e32 v52, v38, v51
	v_fma_f32 v53, -v50, v52, v38
	v_fmac_f32_e32 v52, v53, v51
	v_fma_f32 v38, -v50, v52, v38
	v_div_fmas_f32 v38, v38, v51, v52
	v_div_fixup_f32 v34, v38, v34, 1.0
	v_pk_mul_f32 v[50:51], v[68:69], v[34:35] op_sel_hi:[1,0]
	v_pk_mul_f32 v[42:43], v[42:43], v[34:35] op_sel_hi:[1,0]
	v_mul_f32_e32 v38, 0xbfb8aa3b, v51
	v_mul_f32_e32 v52, 0xbfb8aa3b, v43
	v_exp_f32_e32 v38, v38
	v_exp_f32_e32 v52, v52
	v_pk_mul_f32 v[48:49], v[48:49], v[34:35] op_sel_hi:[1,0]
	v_pk_mul_f32 v[44:45], v[44:45], v[34:35] op_sel_hi:[1,0]
	v_add_f32_e32 v38, 1.0, v38
	v_mul_f32_e32 v55, 0xbfb8aa3b, v49
	v_add_f32_e32 v52, 1.0, v52
	v_rcp_f32_e32 v38, v38
	v_exp_f32_e32 v55, v55
	v_rcp_f32_e32 v52, v52
	v_mul_f32_e32 v54, 0xbfb8aa3b, v45
	v_pk_mul_f32 v[46:47], v[46:47], v[34:35] op_sel_hi:[1,0]
	v_exp_f32_e32 v54, v54
	v_mul_f32_e32 v53, 0xbfb8aa3b, v47
	v_mul_f32_e32 v38, v51, v38
	v_exp_f32_e32 v53, v53
	v_mul_f32_e32 v43, v43, v52
	v_mul_f32_e32 v50, v50, v38
	v_add_f32_e32 v38, 1.0, v55
	v_mul_f32_e32 v51, v42, v43
	v_rcp_f32_e32 v42, v38
	v_mov_b32_e32 v38, v35
	v_add_f32_e32 v54, 1.0, v54
	v_pk_mul_f32 v[38:39], v[38:39], v[34:35] op_sel_hi:[1,0]
	v_rcp_f32_e32 v54, v54
	v_mul_f32_e32 v35, 0xbfb8aa3b, v39
	v_add_f32_e32 v53, 1.0, v53
	v_exp_f32_e32 v35, v35
	v_rcp_f32_e32 v53, v53
	v_mul_f32_e32 v45, v45, v54
	v_mul_f32_e32 v42, v49, v42
	v_mul_f32_e32 v44, v44, v45
	v_mul_f32_e32 v45, v48, v42
	v_add_f32_e32 v35, 1.0, v35
	v_mov_b32_e32 v42, v36
	v_mov_b32_e32 v43, v40
	v_mul_f32_e32 v47, v47, v53
	v_pk_mul_f32 v[42:43], v[42:43], v[34:35] op_sel_hi:[1,0]
	v_mul_f32_e32 v46, v46, v47
	v_rcp_f32_e32 v47, v35
	v_mul_f32_e32 v35, 0xbfb8aa3b, v43
	v_mov_b32_e32 v40, v37
	v_exp_f32_e32 v36, v35
	v_pk_mul_f32 v[34:35], v[40:41], v[34:35] op_sel_hi:[1,0]
	v_mul_f32_e32 v39, v39, v47
	v_mul_f32_e32 v37, 0xbfb8aa3b, v35
	v_exp_f32_e32 v37, v37
	v_add_f32_e32 v36, 1.0, v36
	v_rcp_f32_e32 v36, v36
	v_mul_f32_e32 v38, v38, v39
	v_add_f32_e32 v37, 1.0, v37
	v_rcp_f32_e32 v37, v37
	v_mul_f32_e32 v36, v43, v36
	v_mul_f32_e32 v39, v42, v36
	v_mov_b32_e32 v53, v26
	v_mul_f32_e32 v35, v35, v37
	v_mul_f32_e32 v37, v34, v35
	v_cvt_pk_bf16_f32 v34, v50, v51
	v_cvt_pk_bf16_f32 v35, v46, v44
	v_cvt_pk_bf16_f32 v36, v45, v38
	v_cvt_pk_bf16_f32 v37, v39, v37
	v_mad_i64_i32 v[38:39], s[6:7], v66, s50, v[114:115]
	v_add_u32_e32 v50, 0xa0, v146
	v_lshl_add_u64 v[38:39], v[38:39], 0, v[116:117]
	v_ashrrev_i32_e32 v51, 31, v50
	global_store_dwordx4 v[38:39], v[34:37], off nt
	v_mov_b32_e32 v26, v31
	v_mov_b32_e32 v52, v30
	v_lshlrev_b64 v[34:35], 6, v[50:51]
	v_lshl_add_u64 v[46:47], s[10:11], 0, v[34:35]
	s_waitcnt vmcnt(6)
	v_mov_b32_e32 v34, v176
	v_mov_b32_e32 v35, v177
	v_mov_b32_e32 v36, v178
	v_mov_b32_e32 v37, v179
	v_mov_b32_e32 v38, v180
	v_mov_b32_e32 v39, v181
	v_mov_b32_e32 v40, v182
	v_mov_b32_e32 v41, v183
	v_mov_b32_e32 v42, v184
	v_mov_b32_e32 v43, v185
	v_mov_b32_e32 v44, v186
	v_mov_b32_e32 v45, v187
	v_mov_b32_e32 v46, v188
	v_mov_b32_e32 v47, v189
	v_mov_b32_e32 v48, v190
	v_mov_b32_e32 v49, v191
	v_mov_b32_e32 v30, v32
	v_mov_b32_e32 v54, v35
	v_mov_b32_e32 v55, v36
	v_mov_b32_e32 v35, v37
	v_mov_b32_e32 v36, v39
	v_mov_b32_e32 v37, v40
	v_mov_b32_e32 v39, v41
	v_pk_add_f32 v[34:35], v[54:55], v[34:35]
	v_pk_add_f32 v[36:37], v[36:37], v[38:39]
	v_pk_add_f32 v[34:35], v[34:35], v[34:35] op_sel:[0,1] op_sel_hi:[1,0]
	v_pk_add_f32 v[36:37], v[36:37], v[36:37] op_sel:[0,1] op_sel_hi:[1,0]
	v_add_f32_e32 v40, v42, v43
	v_add_f32_e32 v42, v44, v45
	v_mov_b32_e32 v41, v48
	v_mov_b32_e32 v43, v49
	v_mov_b32_e32 v35, v46
	v_mov_b32_e32 v37, v47
	v_pk_add_f32 v[38:39], v[40:41], v[42:43]
	v_pk_add_f32 v[34:35], v[34:35], v[36:37]
	s_nop 0
	v_pk_add_f32 v[34:35], v[34:35], v[38:39]
	s_nop 0
	v_add_f32_e32 v31, v34, v35
	v_fmamk_f32 v31, v31, 0x3a800000, v152
	v_mul_f32_e32 v32, 0x4f800000, v31
	v_cmp_gt_f32_e32 vcc, s49, v31
	s_nop 1
	v_cndmask_b32_e32 v34, v31, v32, vcc
	v_sqrt_f32_e32 v35, v34
	v_mov_b32_e32 v32, v18
	v_mov_b32_e32 v31, v28
	v_mov_b32_e32 v28, v33
	v_add_u32_e32 v18, -1, v35
	v_add_u32_e32 v33, 1, v35
	v_fma_f32 v36, -v18, v35, v34
	v_fma_f32 v37, -v33, v35, v34
	v_cmp_ge_f32_e64 s[6:7], 0, v36
	s_nop 1
	v_cndmask_b32_e64 v18, v35, v18, s[6:7]
	v_cmp_lt_f32_e64 s[6:7], 0, v37
	s_nop 1
	v_cndmask_b32_e64 v18, v18, v33, s[6:7]
	v_mul_f32_e32 v33, 0x37800000, v18
	v_cndmask_b32_e32 v18, v18, v33, vcc
	v_cmp_class_f32_e32 vcc, v34, v153
	v_mov_b32_e32 v33, v22
	s_nop 0
	v_cndmask_b32_e32 v18, v18, v34, vcc
	v_div_scale_f32 v34, s[6:7], v18, v18, 1.0
	v_rcp_f32_e32 v35, v34
	v_div_scale_f32 v22, vcc, 1.0, v18, 1.0
	v_fma_f32 v36, -v34, v35, 1.0
	v_fmac_f32_e32 v35, v36, v35
	v_mul_f32_e32 v36, v22, v35
	v_fma_f32 v37, -v34, v36, v22
	v_fmac_f32_e32 v36, v37, v35
	v_fma_f32 v22, -v34, v36, v22
	v_div_fmas_f32 v22, v22, v35, v36
	v_div_fixup_f32 v18, v22, v18, 1.0
	v_pk_mul_f32 v[26:27], v[26:27], v[18:19] op_sel_hi:[1,0]
	v_pk_mul_f32 v[34:35], v[52:53], v[18:19] op_sel_hi:[1,0]
	v_mul_f32_e32 v36, 0xbfb8aa3b, v27
	v_mul_f32_e32 v22, 0xbfb8aa3b, v35
	v_exp_f32_e32 v36, v36
	v_exp_f32_e32 v22, v22
	v_pk_mul_f32 v[30:31], v[30:31], v[18:19] op_sel_hi:[1,0]
	v_pk_mul_f32 v[28:29], v[28:29], v[18:19] op_sel_hi:[1,0]
	v_add_f32_e32 v36, 1.0, v36
	v_add_f32_e32 v22, 1.0, v22
	v_rcp_f32_e32 v36, v36
	v_mul_f32_e32 v37, 0xbfb8aa3b, v31
	v_rcp_f32_e32 v22, v22
	v_exp_f32_e32 v37, v37
	v_mul_f32_e32 v27, v27, v36
	v_mul_f32_e32 v38, 0xbfb8aa3b, v29
	v_mul_f32_e32 v22, v35, v22
	v_mul_f32_e32 v35, v26, v27
	v_pk_mul_f32 v[26:27], v[32:33], v[18:19] op_sel_hi:[1,0]
	v_add_f32_e32 v37, 1.0, v37
	v_mul_f32_e32 v34, v34, v22
	v_mul_f32_e32 v22, 0xbfb8aa3b, v27
	v_rcp_f32_e32 v37, v37
	v_exp_f32_e32 v22, v22
	v_exp_f32_e32 v38, v38
	v_mov_b32_e32 v36, v10
	v_mul_f32_e32 v31, v31, v37
	v_add_f32_e32 v22, 1.0, v22
	v_mul_f32_e32 v30, v30, v31
	v_rcp_f32_e32 v31, v22
	v_mov_b32_e32 v22, v19
	v_add_f32_e32 v38, 1.0, v38
	v_pk_mul_f32 v[22:23], v[22:23], v[18:19] op_sel_hi:[1,0]
	v_rcp_f32_e32 v38, v38
	v_mul_f32_e32 v19, 0xbfb8aa3b, v23
	v_exp_f32_e32 v19, v19
	v_mul_f32_e32 v27, v27, v31
	v_mul_f32_e32 v29, v29, v38
	v_mul_f32_e32 v28, v28, v29
	v_mul_f32_e32 v29, v26, v27
	v_add_f32_e32 v19, 1.0, v19
	v_mov_b32_e32 v26, v20
	v_mov_b32_e32 v27, v24
	v_pk_mul_f32 v[26:27], v[26:27], v[18:19] op_sel_hi:[1,0]
	v_rcp_f32_e32 v31, v19
	v_mul_f32_e32 v19, 0xbfb8aa3b, v27
	v_mov_b32_e32 v24, v21
	v_exp_f32_e32 v20, v19
	v_pk_mul_f32 v[18:19], v[24:25], v[18:19] op_sel_hi:[1,0]
	v_mul_f32_e32 v23, v23, v31
	v_mul_f32_e32 v21, 0xbfb8aa3b, v19
	v_exp_f32_e32 v21, v21
	v_add_f32_e32 v20, 1.0, v20
	v_rcp_f32_e32 v20, v20
	v_mul_f32_e32 v22, v22, v23
	v_add_f32_e32 v21, 1.0, v21
	v_rcp_f32_e32 v21, v21
	v_mul_f32_e32 v20, v27, v20
	v_mul_f32_e32 v23, v26, v20
	v_mov_b32_e32 v37, v14
	v_mul_f32_e32 v19, v19, v21
	v_mul_f32_e32 v21, v18, v19
	v_cvt_pk_bf16_f32 v18, v34, v35
	v_cvt_pk_bf16_f32 v19, v30, v28
	v_cvt_pk_bf16_f32 v20, v29, v22
	v_cvt_pk_bf16_f32 v21, v23, v21
	v_mad_i64_i32 v[22:23], s[6:7], v50, s50, v[114:115]
	v_add_u32_e32 v34, 0xb0, v146
	v_lshl_add_u64 v[22:23], v[22:23], 0, v[116:117]
	v_ashrrev_i32_e32 v35, 31, v34
	global_store_dwordx4 v[22:23], v[18:21], off nt
	s_nop 1
	v_lshlrev_b64 v[18:19], 6, v[34:35]
	v_lshl_add_u64 v[30:31], s[10:11], 0, v[18:19]
	s_waitcnt vmcnt(2)
	v_mov_b32_e32 v18, v192
	v_mov_b32_e32 v19, v193
	v_mov_b32_e32 v20, v194
	v_mov_b32_e32 v21, v195
	v_mov_b32_e32 v22, v196
	v_mov_b32_e32 v23, v197
	v_mov_b32_e32 v24, v198
	v_mov_b32_e32 v25, v199
	v_mov_b32_e32 v26, v200
	v_mov_b32_e32 v27, v201
	v_mov_b32_e32 v28, v202
	v_mov_b32_e32 v29, v203
	v_mov_b32_e32 v30, v204
	v_mov_b32_e32 v31, v205
	v_mov_b32_e32 v32, v206
	v_mov_b32_e32 v33, v207
	v_mov_b32_e32 v38, v19
	v_mov_b32_e32 v39, v20
	v_mov_b32_e32 v19, v21
	v_mov_b32_e32 v20, v23
	v_mov_b32_e32 v21, v24
	v_mov_b32_e32 v23, v25
	v_pk_add_f32 v[18:19], v[38:39], v[18:19]
	v_pk_add_f32 v[20:21], v[20:21], v[22:23]
	v_pk_add_f32 v[18:19], v[18:19], v[18:19] op_sel:[0,1] op_sel_hi:[1,0]
	v_pk_add_f32 v[20:21], v[20:21], v[20:21] op_sel:[0,1] op_sel_hi:[1,0]
	v_add_f32_e32 v24, v26, v27
	v_add_f32_e32 v26, v28, v29
	v_mov_b32_e32 v25, v32
	v_mov_b32_e32 v27, v33
	v_mov_b32_e32 v19, v30
	v_mov_b32_e32 v21, v31
	v_pk_add_f32 v[22:23], v[24:25], v[26:27]
	v_pk_add_f32 v[18:19], v[18:19], v[20:21]
	s_nop 0
	v_pk_add_f32 v[18:19], v[18:19], v[22:23]
	s_nop 0
	v_add_f32_e32 v10, v18, v19
	v_fmamk_f32 v10, v10, 0x3a800000, v152
	v_mul_f32_e32 v14, 0x4f800000, v10
	v_cmp_gt_f32_e32 vcc, s49, v10
	s_nop 1
	v_cndmask_b32_e32 v18, v10, v14, vcc
	v_sqrt_f32_e32 v19, v18
	v_mov_b32_e32 v10, v12
	v_mov_b32_e32 v14, v11
	v_mov_b32_e32 v11, v16
	v_add_u32_e32 v12, -1, v19
	v_add_u32_e32 v16, 1, v19
	v_fma_f32 v20, -v12, v19, v18
	v_fma_f32 v21, -v16, v19, v18
	v_cmp_ge_f32_e64 s[6:7], 0, v20
	s_nop 1
	v_cndmask_b32_e64 v12, v19, v12, s[6:7]
	v_cmp_lt_f32_e64 s[6:7], 0, v21
	s_nop 1
	v_cndmask_b32_e64 v12, v12, v16, s[6:7]
	v_mul_f32_e32 v16, 0x37800000, v12
	v_cndmask_b32_e32 v12, v12, v16, vcc
	v_cmp_class_f32_e32 vcc, v18, v153
	v_mov_b32_e32 v16, v13
	s_nop 0
	v_cndmask_b32_e32 v12, v12, v18, vcc
	v_div_scale_f32 v18, s[6:7], v12, v12, 1.0
	v_rcp_f32_e32 v19, v18
	v_div_scale_f32 v13, vcc, 1.0, v12, 1.0
	v_fma_f32 v20, -v18, v19, 1.0
	v_fmac_f32_e32 v19, v20, v19
	v_mul_f32_e32 v20, v13, v19
	v_fma_f32 v21, -v18, v20, v13
	v_fmac_f32_e32 v20, v21, v19
	v_fma_f32 v13, -v18, v20, v13
	v_div_fmas_f32 v13, v13, v19, v20
	v_div_fixup_f32 v12, v13, v12, 1.0
	v_pk_mul_f32 v[18:19], v[36:37], v[12:13] op_sel_hi:[1,0]
	v_pk_mul_f32 v[14:15], v[14:15], v[12:13] op_sel_hi:[1,0]
	v_pk_mul_f32 v[10:11], v[10:11], v[12:13] op_sel_hi:[1,0]
	v_pk_mul_f32 v[16:17], v[16:17], v[12:13] op_sel_hi:[1,0]
	v_mul_f32_e32 v13, 0xbfb8aa3b, v19
	v_mul_f32_e32 v20, 0xbfb8aa3b, v15
	v_exp_f32_e32 v13, v13
	v_exp_f32_e32 v20, v20
	v_mul_f32_e32 v21, 0xbfb8aa3b, v11
	v_mul_f32_e32 v22, 0xbfb8aa3b, v17
	v_add_f32_e32 v13, 1.0, v13
	v_add_f32_e32 v20, 1.0, v20
	v_rcp_f32_e32 v13, v13
	v_rcp_f32_e32 v20, v20
	v_exp_f32_e32 v21, v21
	v_exp_f32_e32 v22, v22
	v_mul_f32_e32 v13, v19, v13
	v_mul_f32_e32 v15, v15, v20
	v_mul_f32_e32 v13, v18, v13
	v_mul_f32_e32 v18, v14, v15
	v_add_f32_e32 v14, 1.0, v21
	v_rcp_f32_e32 v19, v14
	v_add_f32_e32 v14, 1.0, v22
	v_rcp_f32_e32 v20, v14
	v_mov_b32_e32 v14, v2
	v_mov_b32_e32 v15, v6
	v_pk_mul_f32 v[14:15], v[14:15], v[12:13] op_sel_hi:[1,0]
	v_mul_f32_e32 v6, v11, v19
	v_mul_f32_e32 v2, 0xbfb8aa3b, v15
	v_exp_f32_e32 v2, v2
	v_mul_f32_e32 v10, v10, v6
	v_mov_b32_e32 v6, v3
	v_mul_f32_e32 v11, v17, v20
	v_add_f32_e32 v2, 1.0, v2
	v_rcp_f32_e32 v17, v2
	v_pk_mul_f32 v[2:3], v[6:7], v[12:13] op_sel_hi:[1,0]
	v_mul_f32_e32 v11, v16, v11
	v_mul_f32_e32 v6, 0xbfb8aa3b, v3
	v_exp_f32_e32 v6, v6
	v_mul_f32_e32 v7, v15, v17
	v_mul_f32_e32 v14, v14, v7
	v_mov_b32_e32 v7, v8
	v_add_f32_e32 v6, 1.0, v6
	v_rcp_f32_e32 v15, v6
	v_mov_b32_e32 v6, v4
	v_pk_mul_f32 v[6:7], v[6:7], v[12:13] op_sel_hi:[1,0]
	v_mov_b32_e32 v8, v5
	v_mul_f32_e32 v4, 0xbfb8aa3b, v7
	v_exp_f32_e32 v16, v4
	v_pk_mul_f32 v[4:5], v[8:9], v[12:13] op_sel_hi:[1,0]
	v_mul_f32_e32 v3, v3, v15
	v_mul_f32_e32 v8, 0xbfb8aa3b, v5
	v_exp_f32_e32 v8, v8
	v_add_f32_e32 v9, 1.0, v16
	v_rcp_f32_e32 v9, v9
	v_mul_f32_e32 v12, v2, v3
	v_add_f32_e32 v8, 1.0, v8
	v_rcp_f32_e32 v8, v8
	v_mul_f32_e32 v2, v7, v9
	v_mul_f32_e32 v6, v6, v2
	s_andn2_b64 vcc, exec, s[4:5]
	v_mul_f32_e32 v2, v5, v8
	v_mul_f32_e32 v5, v4, v2
	v_cvt_pk_bf16_f32 v2, v13, v18
	v_cvt_pk_bf16_f32 v3, v10, v11
	v_cvt_pk_bf16_f32 v4, v14, v12
	v_cvt_pk_bf16_f32 v5, v6, v5
	v_mad_i64_i32 v[6:7], s[6:7], v34, s50, v[114:115]
	v_lshl_add_u64 v[6:7], v[6:7], 0, v[116:117]
	s_mov_b64 s[4:5], -1
	global_store_dwordx4 v[6:7], v[2:5], off nt
	s_cbranch_vccnz .LBB0_2425
	s_andn2_b64 vcc, exec, s[2:3]
	s_cbranch_vccnz .LBB0_2424
	s_barrier
	s_branch .LBB0_2424
